# v111 + static s_setprio: scan stepper waves prio 3, attention younger half prio 1
# speedup vs baseline: 1.0101x; 1.0101x over previous
.LBB0_639:
	s_and_b32 s20, s95, 1
	s_and_saveexec_b64 s[4:5], s[8:9]
	s_xor_b64 s[18:19], exec, s[4:5]
	s_cbranch_execz .LBB0_641
	s_setprio 3
	s_mul_i32 s4, s20, 0xb400
	s_add_i32 s4, s4, 0
	v_add_u32_e32 v2, s4, v108
	v_lshl_add_u32 v104, v48, 2, s4
	v_lshl_add_u32 v105, s20, 12, v117
	ds_read_b128 v[134:137], v2 offset:256
	ds_read_b128 v[138:141], v2 offset:272
	ds_read_b128 v[142:145], v2 offset:512
	ds_read_b128 v[146:149], v2 offset:528
	ds_read_b128 v[150:153], v2 offset:768
	ds_read_b128 v[154:157], v2 offset:784
	ds_read_b32 v210, v104 offset:1280
	ds_read_b128 v[126:129], v2 offset:0
	ds_read_b128 v[130:133], v2 offset:16
	ds_read_b128 v[158:161], v2 offset:1024
	ds_read_b128 v[162:165], v2 offset:1040
	s_waitcnt lgkmcnt(9)
	v_pk_mul_f32 v[134:135], v[96:97], v[134:135]
	v_pk_mul_f32 v[138:139], v[100:101], v[138:139]
	v_pk_fma_f32 v[134:135], v[98:99], v[136:137], v[134:135]
	v_pk_fma_f32 v[138:139], v[102:103], v[140:141], v[138:139]
	s_nop 0
	v_pk_add_f32 v[134:135], v[134:135], v[138:139]
	s_nop 0
	v_add_f32_e32 v136, v134, v135
	ds_read_b128 v[174:177], v2 offset:1696
	s_nop 0
	v_add_f32_dpp v136, v136, v136 quad_perm:[1,0,3,2] row_mask:0xf bank_mask:0xf bound_ctrl:1
	ds_read_b128 v[178:181], v2 offset:1712
	ds_read_b128 v[182:185], v2 offset:1952
	v_add_f32_dpp v136, v136, v136 quad_perm:[2,3,0,1] row_mask:0xf bank_mask:0xf bound_ctrl:1
	ds_read_b128 v[186:189], v2 offset:1968
	ds_read_b128 v[192:195], v2 offset:2208
	v_add_f32_dpp v136, v136, v136 row_half_mirror row_mask:0xf bank_mask:0xf bound_ctrl:1
	s_waitcnt lgkmcnt(12)
	v_pk_mul_f32 v[142:143], v[142:143], v[136:137] op_sel_hi:[1,0]
	v_pk_mul_f32 v[144:145], v[144:145], v[136:137] op_sel_hi:[1,0]
	v_pk_mul_f32 v[146:147], v[146:147], v[136:137] op_sel_hi:[1,0]
	v_pk_mul_f32 v[148:149], v[148:149], v[136:137] op_sel_hi:[1,0]
	ds_read_b128 v[196:199], v2 offset:2224
	s_waitcnt lgkmcnt(10)
	v_pk_fma_f32 v[142:143], v[150:151], v[210:211], v[142:143] op_sel_hi:[1,0,1]
	v_pk_fma_f32 v[144:145], v[152:153], v[210:211], v[144:145] op_sel_hi:[1,0,1]
	v_pk_fma_f32 v[146:147], v[154:155], v[210:211], v[146:147] op_sel_hi:[1,0,1]
	v_pk_fma_f32 v[148:149], v[156:157], v[210:211], v[148:149] op_sel_hi:[1,0,1]
	ds_read_b32 v212, v104 offset:2720
	ds_read_b128 v[166:169], v2 offset:1440
	s_waitcnt lgkmcnt(10)
	v_pk_fma_f32 v[96:97], v[96:97], v[126:127], v[142:143]
	v_pk_fma_f32 v[98:99], v[98:99], v[128:129], v[144:145]
	v_pk_fma_f32 v[100:101], v[100:101], v[130:131], v[146:147]
	v_pk_fma_f32 v[102:103], v[102:103], v[132:133], v[148:149]
	ds_read_b128 v[170:173], v2 offset:1456
	ds_read_b128 v[200:203], v2 offset:2464
	ds_read_b128 v[204:207], v2 offset:2480
	s_waitcnt lgkmcnt(9)
	v_pk_mul_f32 v[174:175], v[96:97], v[174:175]
	v_pk_mul_f32 v[158:159], v[96:97], v[158:159]
	v_pk_mul_f32 v[178:179], v[100:101], v[178:179]
	v_pk_mul_f32 v[162:163], v[100:101], v[162:163]
	v_pk_fma_f32 v[174:175], v[98:99], v[176:177], v[174:175]
	v_pk_fma_f32 v[158:159], v[98:99], v[160:161], v[158:159]
	v_pk_fma_f32 v[178:179], v[102:103], v[180:181], v[178:179]
	v_pk_fma_f32 v[162:163], v[102:103], v[164:165], v[162:163]
	v_pk_add_f32 v[174:175], v[174:175], v[178:179]
	v_pk_add_f32 v[158:159], v[158:159], v[162:163]
	v_add_f32_e32 v176, v174, v175
	v_add_f32_e32 v211, v158, v159
	ds_read_b128 v[134:137], v2 offset:3136
	v_add_f32_dpp v176, v176, v176 quad_perm:[1,0,3,2] row_mask:0xf bank_mask:0xf bound_ctrl:1
	ds_read_b128 v[138:141], v2 offset:3152
	ds_read_b128 v[142:145], v2 offset:3392
	v_add_f32_dpp v176, v176, v176 quad_perm:[2,3,0,1] row_mask:0xf bank_mask:0xf bound_ctrl:1
	ds_read_b128 v[146:149], v2 offset:3408
	ds_read_b128 v[150:153], v2 offset:3648
	v_add_f32_dpp v176, v176, v176 row_half_mirror row_mask:0xf bank_mask:0xf bound_ctrl:1
	s_waitcnt lgkmcnt(12)
	v_pk_mul_f32 v[182:183], v[182:183], v[176:177] op_sel_hi:[1,0]
	v_pk_mul_f32 v[184:185], v[184:185], v[176:177] op_sel_hi:[1,0]
	v_pk_mul_f32 v[186:187], v[186:187], v[176:177] op_sel_hi:[1,0]
	v_pk_mul_f32 v[188:189], v[188:189], v[176:177] op_sel_hi:[1,0]
	ds_read_b128 v[154:157], v2 offset:3664
	s_waitcnt lgkmcnt(10)
	v_pk_fma_f32 v[182:183], v[192:193], v[212:213], v[182:183] op_sel_hi:[1,0,1]
	v_pk_fma_f32 v[184:185], v[194:195], v[212:213], v[184:185] op_sel_hi:[1,0,1]
	v_pk_fma_f32 v[186:187], v[196:197], v[212:213], v[186:187] op_sel_hi:[1,0,1]
	v_pk_fma_f32 v[188:189], v[198:199], v[212:213], v[188:189] op_sel_hi:[1,0,1]
	ds_read_b32 v210, v104 offset:4160
	ds_read_b128 v[126:129], v2 offset:2880
	s_waitcnt lgkmcnt(10)
	v_pk_fma_f32 v[96:97], v[96:97], v[166:167], v[182:183]
	v_pk_fma_f32 v[98:99], v[98:99], v[168:169], v[184:185]
	v_pk_fma_f32 v[100:101], v[100:101], v[170:171], v[186:187]
	v_pk_fma_f32 v[102:103], v[102:103], v[172:173], v[188:189]
	ds_read_b128 v[130:133], v2 offset:2896
	ds_read_b128 v[158:161], v2 offset:3904
	ds_read_b128 v[162:165], v2 offset:3920
	s_waitcnt lgkmcnt(9)
	v_pk_mul_f32 v[134:135], v[96:97], v[134:135]
	v_pk_mul_f32 v[200:201], v[96:97], v[200:201]
	v_pk_mul_f32 v[138:139], v[100:101], v[138:139]
	v_pk_mul_f32 v[204:205], v[100:101], v[204:205]
	v_pk_fma_f32 v[134:135], v[98:99], v[136:137], v[134:135]
	v_pk_fma_f32 v[200:201], v[98:99], v[202:203], v[200:201]
	v_pk_fma_f32 v[138:139], v[102:103], v[140:141], v[138:139]
	v_pk_fma_f32 v[204:205], v[102:103], v[206:207], v[204:205]
	v_pk_add_f32 v[134:135], v[134:135], v[138:139]
	v_pk_add_f32 v[200:201], v[200:201], v[204:205]
	v_add_f32_e32 v136, v134, v135
	v_add_f32_e32 v213, v200, v201
	ds_read_b128 v[174:177], v2 offset:4576
	v_add_f32_dpp v136, v136, v136 quad_perm:[1,0,3,2] row_mask:0xf bank_mask:0xf bound_ctrl:1
	ds_read_b128 v[178:181], v2 offset:4592
	ds_read_b128 v[182:185], v2 offset:4832
	v_add_f32_dpp v136, v136, v136 quad_perm:[2,3,0,1] row_mask:0xf bank_mask:0xf bound_ctrl:1
	ds_read_b128 v[186:189], v2 offset:4848
	ds_read_b128 v[192:195], v2 offset:5088
	v_add_f32_dpp v136, v136, v136 row_half_mirror row_mask:0xf bank_mask:0xf bound_ctrl:1
	s_waitcnt lgkmcnt(12)
	v_pk_mul_f32 v[142:143], v[142:143], v[136:137] op_sel_hi:[1,0]
	v_pk_mul_f32 v[144:145], v[144:145], v[136:137] op_sel_hi:[1,0]
	v_pk_mul_f32 v[146:147], v[146:147], v[136:137] op_sel_hi:[1,0]
	v_pk_mul_f32 v[148:149], v[148:149], v[136:137] op_sel_hi:[1,0]
	ds_read_b128 v[196:199], v2 offset:5104
	s_waitcnt lgkmcnt(10)
	v_pk_fma_f32 v[142:143], v[150:151], v[210:211], v[142:143] op_sel_hi:[1,0,1]
	v_pk_fma_f32 v[144:145], v[152:153], v[210:211], v[144:145] op_sel_hi:[1,0,1]
	v_pk_fma_f32 v[146:147], v[154:155], v[210:211], v[146:147] op_sel_hi:[1,0,1]
	v_pk_fma_f32 v[148:149], v[156:157], v[210:211], v[148:149] op_sel_hi:[1,0,1]
	ds_read_b32 v212, v104 offset:5600
	ds_read_b128 v[166:169], v2 offset:4320
	s_waitcnt lgkmcnt(10)
	v_pk_fma_f32 v[96:97], v[96:97], v[126:127], v[142:143]
	v_pk_fma_f32 v[98:99], v[98:99], v[128:129], v[144:145]
	v_pk_fma_f32 v[100:101], v[100:101], v[130:131], v[146:147]
	v_pk_fma_f32 v[102:103], v[102:103], v[132:133], v[148:149]
	ds_read_b128 v[170:173], v2 offset:4336
	ds_read_b128 v[200:203], v2 offset:5344
	ds_read_b128 v[204:207], v2 offset:5360
	s_waitcnt lgkmcnt(9)
	v_pk_mul_f32 v[174:175], v[96:97], v[174:175]
	v_pk_mul_f32 v[158:159], v[96:97], v[158:159]
	v_pk_mul_f32 v[178:179], v[100:101], v[178:179]
	v_pk_mul_f32 v[162:163], v[100:101], v[162:163]
	v_pk_fma_f32 v[174:175], v[98:99], v[176:177], v[174:175]
	v_pk_fma_f32 v[158:159], v[98:99], v[160:161], v[158:159]
	v_pk_fma_f32 v[178:179], v[102:103], v[180:181], v[178:179]
	v_pk_fma_f32 v[162:163], v[102:103], v[164:165], v[162:163]
	v_pk_add_f32 v[174:175], v[174:175], v[178:179]
	v_pk_add_f32 v[158:159], v[158:159], v[162:163]
	v_add_f32_e32 v176, v174, v175
	v_add_f32_e32 v214, v158, v159
	ds_read_b128 v[134:137], v2 offset:6016
	v_add_f32_dpp v176, v176, v176 quad_perm:[1,0,3,2] row_mask:0xf bank_mask:0xf bound_ctrl:1
	ds_read_b128 v[138:141], v2 offset:6032
	ds_read_b128 v[142:145], v2 offset:6272
	v_add_f32_dpp v176, v176, v176 quad_perm:[2,3,0,1] row_mask:0xf bank_mask:0xf bound_ctrl:1
	ds_read_b128 v[146:149], v2 offset:6288
	ds_read_b128 v[150:153], v2 offset:6528
	v_add_f32_dpp v176, v176, v176 row_half_mirror row_mask:0xf bank_mask:0xf bound_ctrl:1
	s_waitcnt lgkmcnt(12)
	v_pk_mul_f32 v[182:183], v[182:183], v[176:177] op_sel_hi:[1,0]
	v_pk_mul_f32 v[184:185], v[184:185], v[176:177] op_sel_hi:[1,0]
	v_pk_mul_f32 v[186:187], v[186:187], v[176:177] op_sel_hi:[1,0]
	v_pk_mul_f32 v[188:189], v[188:189], v[176:177] op_sel_hi:[1,0]
	ds_read_b128 v[154:157], v2 offset:6544
	s_waitcnt lgkmcnt(10)
	v_pk_fma_f32 v[182:183], v[192:193], v[212:213], v[182:183] op_sel_hi:[1,0,1]
	v_pk_fma_f32 v[184:185], v[194:195], v[212:213], v[184:185] op_sel_hi:[1,0,1]
	v_pk_fma_f32 v[186:187], v[196:197], v[212:213], v[186:187] op_sel_hi:[1,0,1]
	v_pk_fma_f32 v[188:189], v[198:199], v[212:213], v[188:189] op_sel_hi:[1,0,1]
	ds_read_b32 v210, v104 offset:7040
	ds_read_b128 v[126:129], v2 offset:5760
	s_waitcnt lgkmcnt(10)
	v_pk_fma_f32 v[96:97], v[96:97], v[166:167], v[182:183]
	v_pk_fma_f32 v[98:99], v[98:99], v[168:169], v[184:185]
	v_pk_fma_f32 v[100:101], v[100:101], v[170:171], v[186:187]
	v_pk_fma_f32 v[102:103], v[102:103], v[172:173], v[188:189]
	ds_read_b128 v[130:133], v2 offset:5776
	ds_read_b128 v[158:161], v2 offset:6784
	ds_read_b128 v[162:165], v2 offset:6800
	s_waitcnt lgkmcnt(9)
	v_pk_mul_f32 v[134:135], v[96:97], v[134:135]
	v_pk_mul_f32 v[200:201], v[96:97], v[200:201]
	v_pk_mul_f32 v[138:139], v[100:101], v[138:139]
	v_pk_mul_f32 v[204:205], v[100:101], v[204:205]
	v_pk_fma_f32 v[134:135], v[98:99], v[136:137], v[134:135]
	v_pk_fma_f32 v[200:201], v[98:99], v[202:203], v[200:201]
	v_pk_fma_f32 v[138:139], v[102:103], v[140:141], v[138:139]
	v_pk_fma_f32 v[204:205], v[102:103], v[206:207], v[204:205]
	v_pk_add_f32 v[134:135], v[134:135], v[138:139]
	v_pk_add_f32 v[200:201], v[200:201], v[204:205]
	v_add_f32_e32 v136, v134, v135
	v_add_f32_e32 v215, v200, v201
	ds_read_b128 v[174:177], v2 offset:7456
	v_add_f32_dpp v136, v136, v136 quad_perm:[1,0,3,2] row_mask:0xf bank_mask:0xf bound_ctrl:1
	ds_read_b128 v[178:181], v2 offset:7472
	ds_read_b128 v[182:185], v2 offset:7712
	v_add_f32_dpp v136, v136, v136 quad_perm:[2,3,0,1] row_mask:0xf bank_mask:0xf bound_ctrl:1
	ds_read_b128 v[186:189], v2 offset:7728
	ds_read_b128 v[192:195], v2 offset:7968
	v_add_f32_dpp v136, v136, v136 row_half_mirror row_mask:0xf bank_mask:0xf bound_ctrl:1
	s_waitcnt lgkmcnt(12)
	v_pk_mul_f32 v[142:143], v[142:143], v[136:137] op_sel_hi:[1,0]
	v_pk_mul_f32 v[144:145], v[144:145], v[136:137] op_sel_hi:[1,0]
	v_pk_mul_f32 v[146:147], v[146:147], v[136:137] op_sel_hi:[1,0]
	v_pk_mul_f32 v[148:149], v[148:149], v[136:137] op_sel_hi:[1,0]
	ds_read_b128 v[196:199], v2 offset:7984
	s_waitcnt lgkmcnt(10)
	v_pk_fma_f32 v[142:143], v[150:151], v[210:211], v[142:143] op_sel_hi:[1,0,1]
	v_pk_fma_f32 v[144:145], v[152:153], v[210:211], v[144:145] op_sel_hi:[1,0,1]
	v_pk_fma_f32 v[146:147], v[154:155], v[210:211], v[146:147] op_sel_hi:[1,0,1]
	v_pk_fma_f32 v[148:149], v[156:157], v[210:211], v[148:149] op_sel_hi:[1,0,1]
	ds_read_b32 v212, v104 offset:8480
	ds_read_b128 v[166:169], v2 offset:7200
	s_waitcnt lgkmcnt(10)
	v_pk_fma_f32 v[96:97], v[96:97], v[126:127], v[142:143]
	v_pk_fma_f32 v[98:99], v[98:99], v[128:129], v[144:145]
	v_pk_fma_f32 v[100:101], v[100:101], v[130:131], v[146:147]
	v_pk_fma_f32 v[102:103], v[102:103], v[132:133], v[148:149]
	ds_read_b128 v[170:173], v2 offset:7216
	ds_read_b128 v[200:203], v2 offset:8224
	ds_read_b128 v[204:207], v2 offset:8240
	s_waitcnt lgkmcnt(9)
	v_pk_mul_f32 v[174:175], v[96:97], v[174:175]
	v_pk_mul_f32 v[158:159], v[96:97], v[158:159]
	v_pk_mul_f32 v[178:179], v[100:101], v[178:179]
	v_pk_mul_f32 v[162:163], v[100:101], v[162:163]
	v_pk_fma_f32 v[174:175], v[98:99], v[176:177], v[174:175]
	v_pk_fma_f32 v[158:159], v[98:99], v[160:161], v[158:159]
	v_pk_fma_f32 v[178:179], v[102:103], v[180:181], v[178:179]
	v_pk_fma_f32 v[162:163], v[102:103], v[164:165], v[162:163]
	v_pk_add_f32 v[174:175], v[174:175], v[178:179]
	v_pk_add_f32 v[158:159], v[158:159], v[162:163]
	v_add_f32_e32 v176, v174, v175
	v_add_f32_e32 v216, v158, v159
	ds_read_b128 v[134:137], v2 offset:8896
	v_add_f32_dpp v176, v176, v176 quad_perm:[1,0,3,2] row_mask:0xf bank_mask:0xf bound_ctrl:1
	ds_read_b128 v[138:141], v2 offset:8912
	ds_read_b128 v[142:145], v2 offset:9152
	v_add_f32_dpp v176, v176, v176 quad_perm:[2,3,0,1] row_mask:0xf bank_mask:0xf bound_ctrl:1
	ds_read_b128 v[146:149], v2 offset:9168
	ds_read_b128 v[150:153], v2 offset:9408
	v_add_f32_dpp v176, v176, v176 row_half_mirror row_mask:0xf bank_mask:0xf bound_ctrl:1
	s_waitcnt lgkmcnt(12)
	v_pk_mul_f32 v[182:183], v[182:183], v[176:177] op_sel_hi:[1,0]
	v_pk_mul_f32 v[184:185], v[184:185], v[176:177] op_sel_hi:[1,0]
	v_pk_mul_f32 v[186:187], v[186:187], v[176:177] op_sel_hi:[1,0]
	v_pk_mul_f32 v[188:189], v[188:189], v[176:177] op_sel_hi:[1,0]
	ds_read_b128 v[154:157], v2 offset:9424
	s_waitcnt lgkmcnt(10)
	v_pk_fma_f32 v[182:183], v[192:193], v[212:213], v[182:183] op_sel_hi:[1,0,1]
	v_pk_fma_f32 v[184:185], v[194:195], v[212:213], v[184:185] op_sel_hi:[1,0,1]
	v_pk_fma_f32 v[186:187], v[196:197], v[212:213], v[186:187] op_sel_hi:[1,0,1]
	v_pk_fma_f32 v[188:189], v[198:199], v[212:213], v[188:189] op_sel_hi:[1,0,1]
	ds_read_b32 v210, v104 offset:9920
	ds_read_b128 v[126:129], v2 offset:8640
	s_waitcnt lgkmcnt(10)
	v_pk_fma_f32 v[96:97], v[96:97], v[166:167], v[182:183]
	v_pk_fma_f32 v[98:99], v[98:99], v[168:169], v[184:185]
	v_pk_fma_f32 v[100:101], v[100:101], v[170:171], v[186:187]
	v_pk_fma_f32 v[102:103], v[102:103], v[172:173], v[188:189]
	ds_read_b128 v[130:133], v2 offset:8656
	ds_read_b128 v[158:161], v2 offset:9664
	ds_read_b128 v[162:165], v2 offset:9680
	s_waitcnt lgkmcnt(9)
	v_pk_mul_f32 v[134:135], v[96:97], v[134:135]
	v_pk_mul_f32 v[200:201], v[96:97], v[200:201]
	v_pk_mul_f32 v[138:139], v[100:101], v[138:139]
	v_pk_mul_f32 v[204:205], v[100:101], v[204:205]
	v_pk_fma_f32 v[134:135], v[98:99], v[136:137], v[134:135]
	v_pk_fma_f32 v[200:201], v[98:99], v[202:203], v[200:201]
	v_pk_fma_f32 v[138:139], v[102:103], v[140:141], v[138:139]
	v_pk_fma_f32 v[204:205], v[102:103], v[206:207], v[204:205]
	v_pk_add_f32 v[134:135], v[134:135], v[138:139]
	v_pk_add_f32 v[200:201], v[200:201], v[204:205]
	v_add_f32_e32 v136, v134, v135
	v_add_f32_e32 v208, v200, v201
	ds_read_b128 v[174:177], v2 offset:10336
	v_add_f32_dpp v136, v136, v136 quad_perm:[1,0,3,2] row_mask:0xf bank_mask:0xf bound_ctrl:1
	ds_read_b128 v[178:181], v2 offset:10352
	ds_read_b128 v[182:185], v2 offset:10592
	v_add_f32_dpp v136, v136, v136 quad_perm:[2,3,0,1] row_mask:0xf bank_mask:0xf bound_ctrl:1
	ds_read_b128 v[186:189], v2 offset:10608
	ds_read_b128 v[192:195], v2 offset:10848
	v_add_f32_dpp v136, v136, v136 row_half_mirror row_mask:0xf bank_mask:0xf bound_ctrl:1
	s_waitcnt lgkmcnt(12)
	v_pk_mul_f32 v[142:143], v[142:143], v[136:137] op_sel_hi:[1,0]
	v_pk_mul_f32 v[144:145], v[144:145], v[136:137] op_sel_hi:[1,0]
	v_pk_mul_f32 v[146:147], v[146:147], v[136:137] op_sel_hi:[1,0]
	v_pk_mul_f32 v[148:149], v[148:149], v[136:137] op_sel_hi:[1,0]
	ds_read_b128 v[196:199], v2 offset:10864
	s_waitcnt lgkmcnt(10)
	v_pk_fma_f32 v[142:143], v[150:151], v[210:211], v[142:143] op_sel_hi:[1,0,1]
	v_pk_fma_f32 v[144:145], v[152:153], v[210:211], v[144:145] op_sel_hi:[1,0,1]
	v_pk_fma_f32 v[146:147], v[154:155], v[210:211], v[146:147] op_sel_hi:[1,0,1]
	v_pk_fma_f32 v[148:149], v[156:157], v[210:211], v[148:149] op_sel_hi:[1,0,1]
	ds_read_b32 v212, v104 offset:11360
	ds_read_b128 v[166:169], v2 offset:10080
	s_waitcnt lgkmcnt(10)
	v_pk_fma_f32 v[96:97], v[96:97], v[126:127], v[142:143]
	v_pk_fma_f32 v[98:99], v[98:99], v[128:129], v[144:145]
	v_pk_fma_f32 v[100:101], v[100:101], v[130:131], v[146:147]
	v_pk_fma_f32 v[102:103], v[102:103], v[132:133], v[148:149]
	ds_read_b128 v[170:173], v2 offset:10096
	ds_read_b128 v[200:203], v2 offset:11104
	ds_read_b128 v[204:207], v2 offset:11120
	s_waitcnt lgkmcnt(9)
	v_pk_mul_f32 v[174:175], v[96:97], v[174:175]
	v_pk_mul_f32 v[158:159], v[96:97], v[158:159]
	v_pk_mul_f32 v[178:179], v[100:101], v[178:179]
	v_pk_mul_f32 v[162:163], v[100:101], v[162:163]
	v_pk_fma_f32 v[174:175], v[98:99], v[176:177], v[174:175]
	v_pk_fma_f32 v[158:159], v[98:99], v[160:161], v[158:159]
	v_pk_fma_f32 v[178:179], v[102:103], v[180:181], v[178:179]
	v_pk_fma_f32 v[162:163], v[102:103], v[164:165], v[162:163]
	v_pk_add_f32 v[174:175], v[174:175], v[178:179]
	v_pk_add_f32 v[158:159], v[158:159], v[162:163]
	v_add_f32_e32 v176, v174, v175
	v_add_f32_e32 v191, v158, v159
	ds_read_b128 v[134:137], v2 offset:11776
	v_add_f32_dpp v176, v176, v176 quad_perm:[1,0,3,2] row_mask:0xf bank_mask:0xf bound_ctrl:1
	ds_read_b128 v[138:141], v2 offset:11792
	ds_read_b128 v[142:145], v2 offset:12032
	v_add_f32_dpp v176, v176, v176 quad_perm:[2,3,0,1] row_mask:0xf bank_mask:0xf bound_ctrl:1
	ds_read_b128 v[146:149], v2 offset:12048
	ds_read_b128 v[150:153], v2 offset:12288
	v_add_f32_dpp v176, v176, v176 row_half_mirror row_mask:0xf bank_mask:0xf bound_ctrl:1
	s_waitcnt lgkmcnt(12)
	v_pk_mul_f32 v[182:183], v[182:183], v[176:177] op_sel_hi:[1,0]
	v_pk_mul_f32 v[184:185], v[184:185], v[176:177] op_sel_hi:[1,0]
	v_pk_mul_f32 v[186:187], v[186:187], v[176:177] op_sel_hi:[1,0]
	v_pk_mul_f32 v[188:189], v[188:189], v[176:177] op_sel_hi:[1,0]
	ds_read_b128 v[154:157], v2 offset:12304
	s_waitcnt lgkmcnt(10)
	v_pk_fma_f32 v[182:183], v[192:193], v[212:213], v[182:183] op_sel_hi:[1,0,1]
	v_pk_fma_f32 v[184:185], v[194:195], v[212:213], v[184:185] op_sel_hi:[1,0,1]
	v_pk_fma_f32 v[186:187], v[196:197], v[212:213], v[186:187] op_sel_hi:[1,0,1]
	v_pk_fma_f32 v[188:189], v[198:199], v[212:213], v[188:189] op_sel_hi:[1,0,1]
	ds_read_b32 v210, v104 offset:12800
	ds_read_b128 v[126:129], v2 offset:11520
	s_waitcnt lgkmcnt(10)
	v_pk_fma_f32 v[96:97], v[96:97], v[166:167], v[182:183]
	v_pk_fma_f32 v[98:99], v[98:99], v[168:169], v[184:185]
	v_pk_fma_f32 v[100:101], v[100:101], v[170:171], v[186:187]
	v_pk_fma_f32 v[102:103], v[102:103], v[172:173], v[188:189]
	ds_read_b128 v[130:133], v2 offset:11536
	ds_read_b128 v[158:161], v2 offset:12544
	ds_read_b128 v[162:165], v2 offset:12560
	s_waitcnt lgkmcnt(9)
	v_pk_mul_f32 v[134:135], v[96:97], v[134:135]
	v_pk_mul_f32 v[200:201], v[96:97], v[200:201]
	v_pk_mul_f32 v[138:139], v[100:101], v[138:139]
	v_pk_mul_f32 v[204:205], v[100:101], v[204:205]
	v_pk_fma_f32 v[134:135], v[98:99], v[136:137], v[134:135]
	v_pk_fma_f32 v[200:201], v[98:99], v[202:203], v[200:201]
	v_pk_fma_f32 v[138:139], v[102:103], v[140:141], v[138:139]
	v_pk_fma_f32 v[204:205], v[102:103], v[206:207], v[204:205]
	v_pk_add_f32 v[134:135], v[134:135], v[138:139]
	v_pk_add_f32 v[200:201], v[200:201], v[204:205]
	v_add_f32_e32 v136, v134, v135
	v_add_f32_e32 v59, v200, v201
	ds_read_b128 v[174:177], v2 offset:13216
	v_add_f32_dpp v136, v136, v136 quad_perm:[1,0,3,2] row_mask:0xf bank_mask:0xf bound_ctrl:1
	ds_read_b128 v[178:181], v2 offset:13232
	ds_read_b128 v[182:185], v2 offset:13472
	v_add_f32_dpp v136, v136, v136 quad_perm:[2,3,0,1] row_mask:0xf bank_mask:0xf bound_ctrl:1
	ds_read_b128 v[186:189], v2 offset:13488
	ds_read_b128 v[192:195], v2 offset:13728
	v_add_f32_dpp v136, v136, v136 row_half_mirror row_mask:0xf bank_mask:0xf bound_ctrl:1
	v_cndmask_b32_e64 v200, v213, v211, s[10:11]
	v_cndmask_b32_e64 v204, v211, v213, s[10:11]
	v_cndmask_b32_e64 v201, v215, v214, s[10:11]
	v_cndmask_b32_e64 v205, v214, v215, s[10:11]
	v_cndmask_b32_e64 v202, v208, v216, s[10:11]
	v_cndmask_b32_e64 v206, v216, v208, s[10:11]
	v_cndmask_b32_e64 v203, v59, v191, s[10:11]
	v_cndmask_b32_e64 v207, v191, v59, s[10:11]
	v_add_f32_dpp v200, v204, v200 quad_perm:[1,0,3,2] row_mask:0xf bank_mask:0xf bound_ctrl:1
	v_add_f32_dpp v201, v205, v201 quad_perm:[1,0,3,2] row_mask:0xf bank_mask:0xf bound_ctrl:1
	v_add_f32_dpp v202, v206, v202 quad_perm:[1,0,3,2] row_mask:0xf bank_mask:0xf bound_ctrl:1
	v_add_f32_dpp v203, v207, v203 quad_perm:[1,0,3,2] row_mask:0xf bank_mask:0xf bound_ctrl:1
	v_cndmask_b32_e64 v204, v201, v200, s[12:13]
	v_cndmask_b32_e64 v206, v200, v201, s[12:13]
	v_cndmask_b32_e64 v205, v203, v202, s[12:13]
	v_cndmask_b32_e64 v207, v202, v203, s[12:13]
	v_add_f32_dpp v204, v206, v204 quad_perm:[2,3,0,1] row_mask:0xf bank_mask:0xf bound_ctrl:1
	s_nop 0
	v_add_f32_dpp v205, v207, v205 quad_perm:[2,3,0,1] row_mask:0xf bank_mask:0xf bound_ctrl:1
	v_xor_b32_e32 v202, 4, v121
	v_cndmask_b32_e64 v200, v205, v204, s[14:15]
	v_cndmask_b32_e64 v201, v204, v205, s[14:15]
	v_lshlrev_b32_e32 v202, 2, v202
	ds_bpermute_b32 v201, v202, v201
	s_waitcnt lgkmcnt(0)
	v_add_f32_e32 v200, v200, v201
	ds_write_b32 v105, v200
	v_pk_mul_f32 v[142:143], v[142:143], v[136:137] op_sel_hi:[1,0]
	v_pk_mul_f32 v[144:145], v[144:145], v[136:137] op_sel_hi:[1,0]
	v_pk_mul_f32 v[146:147], v[146:147], v[136:137] op_sel_hi:[1,0]
	v_pk_mul_f32 v[148:149], v[148:149], v[136:137] op_sel_hi:[1,0]
	ds_read_b128 v[196:199], v2 offset:13744
	v_pk_fma_f32 v[142:143], v[150:151], v[210:211], v[142:143] op_sel_hi:[1,0,1]
	v_pk_fma_f32 v[144:145], v[152:153], v[210:211], v[144:145] op_sel_hi:[1,0,1]
	v_pk_fma_f32 v[146:147], v[154:155], v[210:211], v[146:147] op_sel_hi:[1,0,1]
	v_pk_fma_f32 v[148:149], v[156:157], v[210:211], v[148:149] op_sel_hi:[1,0,1]
	ds_read_b32 v212, v104 offset:14240
	ds_read_b128 v[166:169], v2 offset:12960
	v_pk_fma_f32 v[96:97], v[96:97], v[126:127], v[142:143]
	v_pk_fma_f32 v[98:99], v[98:99], v[128:129], v[144:145]
	v_pk_fma_f32 v[100:101], v[100:101], v[130:131], v[146:147]
	v_pk_fma_f32 v[102:103], v[102:103], v[132:133], v[148:149]
	ds_read_b128 v[170:173], v2 offset:12976
	ds_read_b128 v[200:203], v2 offset:13984
	ds_read_b128 v[204:207], v2 offset:14000
	v_pk_mul_f32 v[174:175], v[96:97], v[174:175]
	v_pk_mul_f32 v[158:159], v[96:97], v[158:159]
	v_pk_mul_f32 v[178:179], v[100:101], v[178:179]
	v_pk_mul_f32 v[162:163], v[100:101], v[162:163]
	v_pk_fma_f32 v[174:175], v[98:99], v[176:177], v[174:175]
	v_pk_fma_f32 v[158:159], v[98:99], v[160:161], v[158:159]
	v_pk_fma_f32 v[178:179], v[102:103], v[180:181], v[178:179]
	v_pk_fma_f32 v[162:163], v[102:103], v[164:165], v[162:163]
	v_pk_add_f32 v[174:175], v[174:175], v[178:179]
	v_pk_add_f32 v[158:159], v[158:159], v[162:163]
	v_add_f32_e32 v176, v174, v175
	v_add_f32_e32 v211, v158, v159
	ds_read_b128 v[134:137], v2 offset:14656
	v_add_f32_dpp v176, v176, v176 quad_perm:[1,0,3,2] row_mask:0xf bank_mask:0xf bound_ctrl:1
	ds_read_b128 v[138:141], v2 offset:14672
	ds_read_b128 v[142:145], v2 offset:14912
	v_add_f32_dpp v176, v176, v176 quad_perm:[2,3,0,1] row_mask:0xf bank_mask:0xf bound_ctrl:1
	ds_read_b128 v[146:149], v2 offset:14928
	ds_read_b128 v[150:153], v2 offset:15168
	v_add_f32_dpp v176, v176, v176 row_half_mirror row_mask:0xf bank_mask:0xf bound_ctrl:1
	v_pk_mul_f32 v[182:183], v[182:183], v[176:177] op_sel_hi:[1,0]
	v_pk_mul_f32 v[184:185], v[184:185], v[176:177] op_sel_hi:[1,0]
	v_pk_mul_f32 v[186:187], v[186:187], v[176:177] op_sel_hi:[1,0]
	v_pk_mul_f32 v[188:189], v[188:189], v[176:177] op_sel_hi:[1,0]
	ds_read_b128 v[154:157], v2 offset:15184
	s_waitcnt lgkmcnt(10)
	v_pk_fma_f32 v[182:183], v[192:193], v[212:213], v[182:183] op_sel_hi:[1,0,1]
	v_pk_fma_f32 v[184:185], v[194:195], v[212:213], v[184:185] op_sel_hi:[1,0,1]
	v_pk_fma_f32 v[186:187], v[196:197], v[212:213], v[186:187] op_sel_hi:[1,0,1]
	v_pk_fma_f32 v[188:189], v[198:199], v[212:213], v[188:189] op_sel_hi:[1,0,1]
	ds_read_b32 v210, v104 offset:15680
	ds_read_b128 v[126:129], v2 offset:14400
	s_waitcnt lgkmcnt(10)
	v_pk_fma_f32 v[96:97], v[96:97], v[166:167], v[182:183]
	v_pk_fma_f32 v[98:99], v[98:99], v[168:169], v[184:185]
	v_pk_fma_f32 v[100:101], v[100:101], v[170:171], v[186:187]
	v_pk_fma_f32 v[102:103], v[102:103], v[172:173], v[188:189]
	ds_read_b128 v[130:133], v2 offset:14416
	ds_read_b128 v[158:161], v2 offset:15424
	ds_read_b128 v[162:165], v2 offset:15440
	s_waitcnt lgkmcnt(9)
	v_pk_mul_f32 v[134:135], v[96:97], v[134:135]
	v_pk_mul_f32 v[200:201], v[96:97], v[200:201]
	v_pk_mul_f32 v[138:139], v[100:101], v[138:139]
	v_pk_mul_f32 v[204:205], v[100:101], v[204:205]
	v_pk_fma_f32 v[134:135], v[98:99], v[136:137], v[134:135]
	v_pk_fma_f32 v[200:201], v[98:99], v[202:203], v[200:201]
	v_pk_fma_f32 v[138:139], v[102:103], v[140:141], v[138:139]
	v_pk_fma_f32 v[204:205], v[102:103], v[206:207], v[204:205]
	v_pk_add_f32 v[134:135], v[134:135], v[138:139]
	v_pk_add_f32 v[200:201], v[200:201], v[204:205]
	v_add_f32_e32 v136, v134, v135
	v_add_f32_e32 v213, v200, v201
	ds_read_b128 v[174:177], v2 offset:16096
	v_add_f32_dpp v136, v136, v136 quad_perm:[1,0,3,2] row_mask:0xf bank_mask:0xf bound_ctrl:1
	ds_read_b128 v[178:181], v2 offset:16112
	ds_read_b128 v[182:185], v2 offset:16352
	v_add_f32_dpp v136, v136, v136 quad_perm:[2,3,0,1] row_mask:0xf bank_mask:0xf bound_ctrl:1
	ds_read_b128 v[186:189], v2 offset:16368
	ds_read_b128 v[192:195], v2 offset:16608
	v_add_f32_dpp v136, v136, v136 row_half_mirror row_mask:0xf bank_mask:0xf bound_ctrl:1
	s_waitcnt lgkmcnt(12)
	v_pk_mul_f32 v[142:143], v[142:143], v[136:137] op_sel_hi:[1,0]
	v_pk_mul_f32 v[144:145], v[144:145], v[136:137] op_sel_hi:[1,0]
	v_pk_mul_f32 v[146:147], v[146:147], v[136:137] op_sel_hi:[1,0]
	v_pk_mul_f32 v[148:149], v[148:149], v[136:137] op_sel_hi:[1,0]
	ds_read_b128 v[196:199], v2 offset:16624
	s_waitcnt lgkmcnt(10)
	v_pk_fma_f32 v[142:143], v[150:151], v[210:211], v[142:143] op_sel_hi:[1,0,1]
	v_pk_fma_f32 v[144:145], v[152:153], v[210:211], v[144:145] op_sel_hi:[1,0,1]
	v_pk_fma_f32 v[146:147], v[154:155], v[210:211], v[146:147] op_sel_hi:[1,0,1]
	v_pk_fma_f32 v[148:149], v[156:157], v[210:211], v[148:149] op_sel_hi:[1,0,1]
	ds_read_b32 v212, v104 offset:17120
	ds_read_b128 v[166:169], v2 offset:15840
	s_waitcnt lgkmcnt(10)
	v_pk_fma_f32 v[96:97], v[96:97], v[126:127], v[142:143]
	v_pk_fma_f32 v[98:99], v[98:99], v[128:129], v[144:145]
	v_pk_fma_f32 v[100:101], v[100:101], v[130:131], v[146:147]
	v_pk_fma_f32 v[102:103], v[102:103], v[132:133], v[148:149]
	ds_read_b128 v[170:173], v2 offset:15856
	ds_read_b128 v[200:203], v2 offset:16864
	ds_read_b128 v[204:207], v2 offset:16880
	s_waitcnt lgkmcnt(9)
	v_pk_mul_f32 v[174:175], v[96:97], v[174:175]
	v_pk_mul_f32 v[158:159], v[96:97], v[158:159]
	v_pk_mul_f32 v[178:179], v[100:101], v[178:179]
	v_pk_mul_f32 v[162:163], v[100:101], v[162:163]
	v_pk_fma_f32 v[174:175], v[98:99], v[176:177], v[174:175]
	v_pk_fma_f32 v[158:159], v[98:99], v[160:161], v[158:159]
	v_pk_fma_f32 v[178:179], v[102:103], v[180:181], v[178:179]
	v_pk_fma_f32 v[162:163], v[102:103], v[164:165], v[162:163]
	v_pk_add_f32 v[174:175], v[174:175], v[178:179]
	v_pk_add_f32 v[158:159], v[158:159], v[162:163]
	v_add_f32_e32 v176, v174, v175
	v_add_f32_e32 v214, v158, v159
	ds_read_b128 v[134:137], v2 offset:17536
	v_add_f32_dpp v176, v176, v176 quad_perm:[1,0,3,2] row_mask:0xf bank_mask:0xf bound_ctrl:1
	ds_read_b128 v[138:141], v2 offset:17552
	ds_read_b128 v[142:145], v2 offset:17792
	v_add_f32_dpp v176, v176, v176 quad_perm:[2,3,0,1] row_mask:0xf bank_mask:0xf bound_ctrl:1
	ds_read_b128 v[146:149], v2 offset:17808
	ds_read_b128 v[150:153], v2 offset:18048
	v_add_f32_dpp v176, v176, v176 row_half_mirror row_mask:0xf bank_mask:0xf bound_ctrl:1
	s_waitcnt lgkmcnt(12)
	v_pk_mul_f32 v[182:183], v[182:183], v[176:177] op_sel_hi:[1,0]
	v_pk_mul_f32 v[184:185], v[184:185], v[176:177] op_sel_hi:[1,0]
	v_pk_mul_f32 v[186:187], v[186:187], v[176:177] op_sel_hi:[1,0]
	v_pk_mul_f32 v[188:189], v[188:189], v[176:177] op_sel_hi:[1,0]
	ds_read_b128 v[154:157], v2 offset:18064
	s_waitcnt lgkmcnt(10)
	v_pk_fma_f32 v[182:183], v[192:193], v[212:213], v[182:183] op_sel_hi:[1,0,1]
	v_pk_fma_f32 v[184:185], v[194:195], v[212:213], v[184:185] op_sel_hi:[1,0,1]
	v_pk_fma_f32 v[186:187], v[196:197], v[212:213], v[186:187] op_sel_hi:[1,0,1]
	v_pk_fma_f32 v[188:189], v[198:199], v[212:213], v[188:189] op_sel_hi:[1,0,1]
	ds_read_b32 v210, v104 offset:18560
	ds_read_b128 v[126:129], v2 offset:17280
	s_waitcnt lgkmcnt(10)
	v_pk_fma_f32 v[96:97], v[96:97], v[166:167], v[182:183]
	v_pk_fma_f32 v[98:99], v[98:99], v[168:169], v[184:185]
	v_pk_fma_f32 v[100:101], v[100:101], v[170:171], v[186:187]
	v_pk_fma_f32 v[102:103], v[102:103], v[172:173], v[188:189]
	ds_read_b128 v[130:133], v2 offset:17296
	ds_read_b128 v[158:161], v2 offset:18304
	ds_read_b128 v[162:165], v2 offset:18320
	s_waitcnt lgkmcnt(9)
	v_pk_mul_f32 v[134:135], v[96:97], v[134:135]
	v_pk_mul_f32 v[200:201], v[96:97], v[200:201]
	v_pk_mul_f32 v[138:139], v[100:101], v[138:139]
	v_pk_mul_f32 v[204:205], v[100:101], v[204:205]
	v_pk_fma_f32 v[134:135], v[98:99], v[136:137], v[134:135]
	v_pk_fma_f32 v[200:201], v[98:99], v[202:203], v[200:201]
	v_pk_fma_f32 v[138:139], v[102:103], v[140:141], v[138:139]
	v_pk_fma_f32 v[204:205], v[102:103], v[206:207], v[204:205]
	v_pk_add_f32 v[134:135], v[134:135], v[138:139]
	v_pk_add_f32 v[200:201], v[200:201], v[204:205]
	v_add_f32_e32 v136, v134, v135
	v_add_f32_e32 v215, v200, v201
	ds_read_b128 v[174:177], v2 offset:18976
	v_add_f32_dpp v136, v136, v136 quad_perm:[1,0,3,2] row_mask:0xf bank_mask:0xf bound_ctrl:1
	ds_read_b128 v[178:181], v2 offset:18992
	ds_read_b128 v[182:185], v2 offset:19232
	v_add_f32_dpp v136, v136, v136 quad_perm:[2,3,0,1] row_mask:0xf bank_mask:0xf bound_ctrl:1
	ds_read_b128 v[186:189], v2 offset:19248
	ds_read_b128 v[192:195], v2 offset:19488
	v_add_f32_dpp v136, v136, v136 row_half_mirror row_mask:0xf bank_mask:0xf bound_ctrl:1
	s_waitcnt lgkmcnt(12)
	v_pk_mul_f32 v[142:143], v[142:143], v[136:137] op_sel_hi:[1,0]
	v_pk_mul_f32 v[144:145], v[144:145], v[136:137] op_sel_hi:[1,0]
	v_pk_mul_f32 v[146:147], v[146:147], v[136:137] op_sel_hi:[1,0]
	v_pk_mul_f32 v[148:149], v[148:149], v[136:137] op_sel_hi:[1,0]
	ds_read_b128 v[196:199], v2 offset:19504
	s_waitcnt lgkmcnt(10)
	v_pk_fma_f32 v[142:143], v[150:151], v[210:211], v[142:143] op_sel_hi:[1,0,1]
	v_pk_fma_f32 v[144:145], v[152:153], v[210:211], v[144:145] op_sel_hi:[1,0,1]
	v_pk_fma_f32 v[146:147], v[154:155], v[210:211], v[146:147] op_sel_hi:[1,0,1]
	v_pk_fma_f32 v[148:149], v[156:157], v[210:211], v[148:149] op_sel_hi:[1,0,1]
	ds_read_b32 v212, v104 offset:20000
	ds_read_b128 v[166:169], v2 offset:18720
	s_waitcnt lgkmcnt(10)
	v_pk_fma_f32 v[96:97], v[96:97], v[126:127], v[142:143]
	v_pk_fma_f32 v[98:99], v[98:99], v[128:129], v[144:145]
	v_pk_fma_f32 v[100:101], v[100:101], v[130:131], v[146:147]
	v_pk_fma_f32 v[102:103], v[102:103], v[132:133], v[148:149]
	ds_read_b128 v[170:173], v2 offset:18736
	ds_read_b128 v[200:203], v2 offset:19744
	ds_read_b128 v[204:207], v2 offset:19760
	s_waitcnt lgkmcnt(9)
	v_pk_mul_f32 v[174:175], v[96:97], v[174:175]
	v_pk_mul_f32 v[158:159], v[96:97], v[158:159]
	v_pk_mul_f32 v[178:179], v[100:101], v[178:179]
	v_pk_mul_f32 v[162:163], v[100:101], v[162:163]
	v_pk_fma_f32 v[174:175], v[98:99], v[176:177], v[174:175]
	v_pk_fma_f32 v[158:159], v[98:99], v[160:161], v[158:159]
	v_pk_fma_f32 v[178:179], v[102:103], v[180:181], v[178:179]
	v_pk_fma_f32 v[162:163], v[102:103], v[164:165], v[162:163]
	v_pk_add_f32 v[174:175], v[174:175], v[178:179]
	v_pk_add_f32 v[158:159], v[158:159], v[162:163]
	v_add_f32_e32 v176, v174, v175
	v_add_f32_e32 v216, v158, v159
	ds_read_b128 v[134:137], v2 offset:20416
	v_add_f32_dpp v176, v176, v176 quad_perm:[1,0,3,2] row_mask:0xf bank_mask:0xf bound_ctrl:1
	ds_read_b128 v[138:141], v2 offset:20432
	ds_read_b128 v[142:145], v2 offset:20672
	v_add_f32_dpp v176, v176, v176 quad_perm:[2,3,0,1] row_mask:0xf bank_mask:0xf bound_ctrl:1
	ds_read_b128 v[146:149], v2 offset:20688
	ds_read_b128 v[150:153], v2 offset:20928
	v_add_f32_dpp v176, v176, v176 row_half_mirror row_mask:0xf bank_mask:0xf bound_ctrl:1
	s_waitcnt lgkmcnt(12)
	v_pk_mul_f32 v[182:183], v[182:183], v[176:177] op_sel_hi:[1,0]
	v_pk_mul_f32 v[184:185], v[184:185], v[176:177] op_sel_hi:[1,0]
	v_pk_mul_f32 v[186:187], v[186:187], v[176:177] op_sel_hi:[1,0]
	v_pk_mul_f32 v[188:189], v[188:189], v[176:177] op_sel_hi:[1,0]
	ds_read_b128 v[154:157], v2 offset:20944
	s_waitcnt lgkmcnt(10)
	v_pk_fma_f32 v[182:183], v[192:193], v[212:213], v[182:183] op_sel_hi:[1,0,1]
	v_pk_fma_f32 v[184:185], v[194:195], v[212:213], v[184:185] op_sel_hi:[1,0,1]
	v_pk_fma_f32 v[186:187], v[196:197], v[212:213], v[186:187] op_sel_hi:[1,0,1]
	v_pk_fma_f32 v[188:189], v[198:199], v[212:213], v[188:189] op_sel_hi:[1,0,1]
	ds_read_b32 v210, v104 offset:21440
	ds_read_b128 v[126:129], v2 offset:20160
	s_waitcnt lgkmcnt(10)
	v_pk_fma_f32 v[96:97], v[96:97], v[166:167], v[182:183]
	v_pk_fma_f32 v[98:99], v[98:99], v[168:169], v[184:185]
	v_pk_fma_f32 v[100:101], v[100:101], v[170:171], v[186:187]
	v_pk_fma_f32 v[102:103], v[102:103], v[172:173], v[188:189]
	ds_read_b128 v[130:133], v2 offset:20176
	ds_read_b128 v[158:161], v2 offset:21184
	ds_read_b128 v[162:165], v2 offset:21200
	s_waitcnt lgkmcnt(9)
	v_pk_mul_f32 v[134:135], v[96:97], v[134:135]
	v_pk_mul_f32 v[200:201], v[96:97], v[200:201]
	v_pk_mul_f32 v[138:139], v[100:101], v[138:139]
	v_pk_mul_f32 v[204:205], v[100:101], v[204:205]
	v_pk_fma_f32 v[134:135], v[98:99], v[136:137], v[134:135]
	v_pk_fma_f32 v[200:201], v[98:99], v[202:203], v[200:201]
	v_pk_fma_f32 v[138:139], v[102:103], v[140:141], v[138:139]
	v_pk_fma_f32 v[204:205], v[102:103], v[206:207], v[204:205]
	v_pk_add_f32 v[134:135], v[134:135], v[138:139]
	v_pk_add_f32 v[200:201], v[200:201], v[204:205]
	v_add_f32_e32 v136, v134, v135
	v_add_f32_e32 v208, v200, v201
	ds_read_b128 v[174:177], v2 offset:21856
	v_add_f32_dpp v136, v136, v136 quad_perm:[1,0,3,2] row_mask:0xf bank_mask:0xf bound_ctrl:1
	ds_read_b128 v[178:181], v2 offset:21872
	ds_read_b128 v[182:185], v2 offset:22112
	v_add_f32_dpp v136, v136, v136 quad_perm:[2,3,0,1] row_mask:0xf bank_mask:0xf bound_ctrl:1
	ds_read_b128 v[186:189], v2 offset:22128
	ds_read_b128 v[192:195], v2 offset:22368
	v_add_f32_dpp v136, v136, v136 row_half_mirror row_mask:0xf bank_mask:0xf bound_ctrl:1
	s_waitcnt lgkmcnt(12)
	v_pk_mul_f32 v[142:143], v[142:143], v[136:137] op_sel_hi:[1,0]
	v_pk_mul_f32 v[144:145], v[144:145], v[136:137] op_sel_hi:[1,0]
	v_pk_mul_f32 v[146:147], v[146:147], v[136:137] op_sel_hi:[1,0]
	v_pk_mul_f32 v[148:149], v[148:149], v[136:137] op_sel_hi:[1,0]
	ds_read_b128 v[196:199], v2 offset:22384
	s_waitcnt lgkmcnt(10)
	v_pk_fma_f32 v[142:143], v[150:151], v[210:211], v[142:143] op_sel_hi:[1,0,1]
	v_pk_fma_f32 v[144:145], v[152:153], v[210:211], v[144:145] op_sel_hi:[1,0,1]
	v_pk_fma_f32 v[146:147], v[154:155], v[210:211], v[146:147] op_sel_hi:[1,0,1]
	v_pk_fma_f32 v[148:149], v[156:157], v[210:211], v[148:149] op_sel_hi:[1,0,1]
	ds_read_b32 v212, v104 offset:22880
	ds_read_b128 v[166:169], v2 offset:21600
	s_waitcnt lgkmcnt(10)
	v_pk_fma_f32 v[96:97], v[96:97], v[126:127], v[142:143]
	v_pk_fma_f32 v[98:99], v[98:99], v[128:129], v[144:145]
	v_pk_fma_f32 v[100:101], v[100:101], v[130:131], v[146:147]
	v_pk_fma_f32 v[102:103], v[102:103], v[132:133], v[148:149]
	ds_read_b128 v[170:173], v2 offset:21616
	ds_read_b128 v[200:203], v2 offset:22624
	ds_read_b128 v[204:207], v2 offset:22640
	s_waitcnt lgkmcnt(9)
	v_pk_mul_f32 v[174:175], v[96:97], v[174:175]
	v_pk_mul_f32 v[158:159], v[96:97], v[158:159]
	v_pk_mul_f32 v[178:179], v[100:101], v[178:179]
	v_pk_mul_f32 v[162:163], v[100:101], v[162:163]
	v_pk_fma_f32 v[174:175], v[98:99], v[176:177], v[174:175]
	v_pk_fma_f32 v[158:159], v[98:99], v[160:161], v[158:159]
	v_pk_fma_f32 v[178:179], v[102:103], v[180:181], v[178:179]
	v_pk_fma_f32 v[162:163], v[102:103], v[164:165], v[162:163]
	v_pk_add_f32 v[174:175], v[174:175], v[178:179]
	v_pk_add_f32 v[158:159], v[158:159], v[162:163]
	v_add_f32_e32 v176, v174, v175
	v_add_f32_e32 v191, v158, v159
	ds_read_b128 v[134:137], v2 offset:23296
	v_add_f32_dpp v176, v176, v176 quad_perm:[1,0,3,2] row_mask:0xf bank_mask:0xf bound_ctrl:1
	ds_read_b128 v[138:141], v2 offset:23312
	ds_read_b128 v[142:145], v2 offset:23552
	v_add_f32_dpp v176, v176, v176 quad_perm:[2,3,0,1] row_mask:0xf bank_mask:0xf bound_ctrl:1
	ds_read_b128 v[146:149], v2 offset:23568
	ds_read_b128 v[150:153], v2 offset:23808
	v_add_f32_dpp v176, v176, v176 row_half_mirror row_mask:0xf bank_mask:0xf bound_ctrl:1
	s_waitcnt lgkmcnt(12)
	v_pk_mul_f32 v[182:183], v[182:183], v[176:177] op_sel_hi:[1,0]
	v_pk_mul_f32 v[184:185], v[184:185], v[176:177] op_sel_hi:[1,0]
	v_pk_mul_f32 v[186:187], v[186:187], v[176:177] op_sel_hi:[1,0]
	v_pk_mul_f32 v[188:189], v[188:189], v[176:177] op_sel_hi:[1,0]
	ds_read_b128 v[154:157], v2 offset:23824
	s_waitcnt lgkmcnt(10)
	v_pk_fma_f32 v[182:183], v[192:193], v[212:213], v[182:183] op_sel_hi:[1,0,1]
	v_pk_fma_f32 v[184:185], v[194:195], v[212:213], v[184:185] op_sel_hi:[1,0,1]
	v_pk_fma_f32 v[186:187], v[196:197], v[212:213], v[186:187] op_sel_hi:[1,0,1]
	v_pk_fma_f32 v[188:189], v[198:199], v[212:213], v[188:189] op_sel_hi:[1,0,1]
	ds_read_b32 v210, v104 offset:24320
	ds_read_b128 v[126:129], v2 offset:23040
	s_waitcnt lgkmcnt(10)
	v_pk_fma_f32 v[96:97], v[96:97], v[166:167], v[182:183]
	v_pk_fma_f32 v[98:99], v[98:99], v[168:169], v[184:185]
	v_pk_fma_f32 v[100:101], v[100:101], v[170:171], v[186:187]
	v_pk_fma_f32 v[102:103], v[102:103], v[172:173], v[188:189]
	ds_read_b128 v[130:133], v2 offset:23056
	ds_read_b128 v[158:161], v2 offset:24064
	ds_read_b128 v[162:165], v2 offset:24080
	s_waitcnt lgkmcnt(9)
	v_pk_mul_f32 v[134:135], v[96:97], v[134:135]
	v_pk_mul_f32 v[200:201], v[96:97], v[200:201]
	v_pk_mul_f32 v[138:139], v[100:101], v[138:139]
	v_pk_mul_f32 v[204:205], v[100:101], v[204:205]
	v_pk_fma_f32 v[134:135], v[98:99], v[136:137], v[134:135]
	v_pk_fma_f32 v[200:201], v[98:99], v[202:203], v[200:201]
	v_pk_fma_f32 v[138:139], v[102:103], v[140:141], v[138:139]
	v_pk_fma_f32 v[204:205], v[102:103], v[206:207], v[204:205]
	v_pk_add_f32 v[134:135], v[134:135], v[138:139]
	v_pk_add_f32 v[200:201], v[200:201], v[204:205]
	v_add_f32_e32 v136, v134, v135
	v_add_f32_e32 v59, v200, v201
	ds_read_b128 v[174:177], v2 offset:24736
	v_add_f32_dpp v136, v136, v136 quad_perm:[1,0,3,2] row_mask:0xf bank_mask:0xf bound_ctrl:1
	ds_read_b128 v[178:181], v2 offset:24752
	ds_read_b128 v[182:185], v2 offset:24992
	v_add_f32_dpp v136, v136, v136 quad_perm:[2,3,0,1] row_mask:0xf bank_mask:0xf bound_ctrl:1
	ds_read_b128 v[186:189], v2 offset:25008
	ds_read_b128 v[192:195], v2 offset:25248
	v_add_f32_dpp v136, v136, v136 row_half_mirror row_mask:0xf bank_mask:0xf bound_ctrl:1
	v_cndmask_b32_e64 v200, v213, v211, s[10:11]
	v_cndmask_b32_e64 v204, v211, v213, s[10:11]
	v_cndmask_b32_e64 v201, v215, v214, s[10:11]
	v_cndmask_b32_e64 v205, v214, v215, s[10:11]
	v_cndmask_b32_e64 v202, v208, v216, s[10:11]
	v_cndmask_b32_e64 v206, v216, v208, s[10:11]
	v_cndmask_b32_e64 v203, v59, v191, s[10:11]
	v_cndmask_b32_e64 v207, v191, v59, s[10:11]
	v_add_f32_dpp v200, v204, v200 quad_perm:[1,0,3,2] row_mask:0xf bank_mask:0xf bound_ctrl:1
	v_add_f32_dpp v201, v205, v201 quad_perm:[1,0,3,2] row_mask:0xf bank_mask:0xf bound_ctrl:1
	v_add_f32_dpp v202, v206, v202 quad_perm:[1,0,3,2] row_mask:0xf bank_mask:0xf bound_ctrl:1
	v_add_f32_dpp v203, v207, v203 quad_perm:[1,0,3,2] row_mask:0xf bank_mask:0xf bound_ctrl:1
	v_cndmask_b32_e64 v204, v201, v200, s[12:13]
	v_cndmask_b32_e64 v206, v200, v201, s[12:13]
	v_cndmask_b32_e64 v205, v203, v202, s[12:13]
	v_cndmask_b32_e64 v207, v202, v203, s[12:13]
	v_add_f32_dpp v204, v206, v204 quad_perm:[2,3,0,1] row_mask:0xf bank_mask:0xf bound_ctrl:1
	s_nop 0
	v_add_f32_dpp v205, v207, v205 quad_perm:[2,3,0,1] row_mask:0xf bank_mask:0xf bound_ctrl:1
	v_xor_b32_e32 v202, 4, v121
	v_cndmask_b32_e64 v200, v205, v204, s[14:15]
	v_cndmask_b32_e64 v201, v204, v205, s[14:15]
	v_lshlrev_b32_e32 v202, 2, v202
	ds_bpermute_b32 v201, v202, v201
	s_waitcnt lgkmcnt(0)
	v_add_f32_e32 v200, v200, v201
	ds_write_b32 v105, v200 offset:1024
	v_pk_mul_f32 v[142:143], v[142:143], v[136:137] op_sel_hi:[1,0]
	v_pk_mul_f32 v[144:145], v[144:145], v[136:137] op_sel_hi:[1,0]
	v_pk_mul_f32 v[146:147], v[146:147], v[136:137] op_sel_hi:[1,0]
	v_pk_mul_f32 v[148:149], v[148:149], v[136:137] op_sel_hi:[1,0]
	ds_read_b128 v[196:199], v2 offset:25264
	v_pk_fma_f32 v[142:143], v[150:151], v[210:211], v[142:143] op_sel_hi:[1,0,1]
	v_pk_fma_f32 v[144:145], v[152:153], v[210:211], v[144:145] op_sel_hi:[1,0,1]
	v_pk_fma_f32 v[146:147], v[154:155], v[210:211], v[146:147] op_sel_hi:[1,0,1]
	v_pk_fma_f32 v[148:149], v[156:157], v[210:211], v[148:149] op_sel_hi:[1,0,1]
	ds_read_b32 v212, v104 offset:25760
	ds_read_b128 v[166:169], v2 offset:24480
	v_pk_fma_f32 v[96:97], v[96:97], v[126:127], v[142:143]
	v_pk_fma_f32 v[98:99], v[98:99], v[128:129], v[144:145]
	v_pk_fma_f32 v[100:101], v[100:101], v[130:131], v[146:147]
	v_pk_fma_f32 v[102:103], v[102:103], v[132:133], v[148:149]
	ds_read_b128 v[170:173], v2 offset:24496
	ds_read_b128 v[200:203], v2 offset:25504
	ds_read_b128 v[204:207], v2 offset:25520
	v_pk_mul_f32 v[174:175], v[96:97], v[174:175]
	v_pk_mul_f32 v[158:159], v[96:97], v[158:159]
	v_pk_mul_f32 v[178:179], v[100:101], v[178:179]
	v_pk_mul_f32 v[162:163], v[100:101], v[162:163]
	v_pk_fma_f32 v[174:175], v[98:99], v[176:177], v[174:175]
	v_pk_fma_f32 v[158:159], v[98:99], v[160:161], v[158:159]
	v_pk_fma_f32 v[178:179], v[102:103], v[180:181], v[178:179]
	v_pk_fma_f32 v[162:163], v[102:103], v[164:165], v[162:163]
	v_pk_add_f32 v[174:175], v[174:175], v[178:179]
	v_pk_add_f32 v[158:159], v[158:159], v[162:163]
	v_add_f32_e32 v176, v174, v175
	v_add_f32_e32 v211, v158, v159
	ds_read_b128 v[134:137], v2 offset:26176
	v_add_f32_dpp v176, v176, v176 quad_perm:[1,0,3,2] row_mask:0xf bank_mask:0xf bound_ctrl:1
	ds_read_b128 v[138:141], v2 offset:26192
	ds_read_b128 v[142:145], v2 offset:26432
	v_add_f32_dpp v176, v176, v176 quad_perm:[2,3,0,1] row_mask:0xf bank_mask:0xf bound_ctrl:1
	ds_read_b128 v[146:149], v2 offset:26448
	ds_read_b128 v[150:153], v2 offset:26688
	v_add_f32_dpp v176, v176, v176 row_half_mirror row_mask:0xf bank_mask:0xf bound_ctrl:1
	v_pk_mul_f32 v[182:183], v[182:183], v[176:177] op_sel_hi:[1,0]
	v_pk_mul_f32 v[184:185], v[184:185], v[176:177] op_sel_hi:[1,0]
	v_pk_mul_f32 v[186:187], v[186:187], v[176:177] op_sel_hi:[1,0]
	v_pk_mul_f32 v[188:189], v[188:189], v[176:177] op_sel_hi:[1,0]
	ds_read_b128 v[154:157], v2 offset:26704
	s_waitcnt lgkmcnt(10)
	v_pk_fma_f32 v[182:183], v[192:193], v[212:213], v[182:183] op_sel_hi:[1,0,1]
	v_pk_fma_f32 v[184:185], v[194:195], v[212:213], v[184:185] op_sel_hi:[1,0,1]
	v_pk_fma_f32 v[186:187], v[196:197], v[212:213], v[186:187] op_sel_hi:[1,0,1]
	v_pk_fma_f32 v[188:189], v[198:199], v[212:213], v[188:189] op_sel_hi:[1,0,1]
	ds_read_b32 v210, v104 offset:27200
	ds_read_b128 v[126:129], v2 offset:25920
	s_waitcnt lgkmcnt(10)
	v_pk_fma_f32 v[96:97], v[96:97], v[166:167], v[182:183]
	v_pk_fma_f32 v[98:99], v[98:99], v[168:169], v[184:185]
	v_pk_fma_f32 v[100:101], v[100:101], v[170:171], v[186:187]
	v_pk_fma_f32 v[102:103], v[102:103], v[172:173], v[188:189]
	ds_read_b128 v[130:133], v2 offset:25936
	ds_read_b128 v[158:161], v2 offset:26944
	ds_read_b128 v[162:165], v2 offset:26960
	s_waitcnt lgkmcnt(9)
	v_pk_mul_f32 v[134:135], v[96:97], v[134:135]
	v_pk_mul_f32 v[200:201], v[96:97], v[200:201]
	v_pk_mul_f32 v[138:139], v[100:101], v[138:139]
	v_pk_mul_f32 v[204:205], v[100:101], v[204:205]
	v_pk_fma_f32 v[134:135], v[98:99], v[136:137], v[134:135]
	v_pk_fma_f32 v[200:201], v[98:99], v[202:203], v[200:201]
	v_pk_fma_f32 v[138:139], v[102:103], v[140:141], v[138:139]
	v_pk_fma_f32 v[204:205], v[102:103], v[206:207], v[204:205]
	v_pk_add_f32 v[134:135], v[134:135], v[138:139]
	v_pk_add_f32 v[200:201], v[200:201], v[204:205]
	v_add_f32_e32 v136, v134, v135
	v_add_f32_e32 v213, v200, v201
	ds_read_b128 v[174:177], v2 offset:27616
	v_add_f32_dpp v136, v136, v136 quad_perm:[1,0,3,2] row_mask:0xf bank_mask:0xf bound_ctrl:1
	ds_read_b128 v[178:181], v2 offset:27632
	ds_read_b128 v[182:185], v2 offset:27872
	v_add_f32_dpp v136, v136, v136 quad_perm:[2,3,0,1] row_mask:0xf bank_mask:0xf bound_ctrl:1
	ds_read_b128 v[186:189], v2 offset:27888
	ds_read_b128 v[192:195], v2 offset:28128
	v_add_f32_dpp v136, v136, v136 row_half_mirror row_mask:0xf bank_mask:0xf bound_ctrl:1
	s_waitcnt lgkmcnt(12)
	v_pk_mul_f32 v[142:143], v[142:143], v[136:137] op_sel_hi:[1,0]
	v_pk_mul_f32 v[144:145], v[144:145], v[136:137] op_sel_hi:[1,0]
	v_pk_mul_f32 v[146:147], v[146:147], v[136:137] op_sel_hi:[1,0]
	v_pk_mul_f32 v[148:149], v[148:149], v[136:137] op_sel_hi:[1,0]
	ds_read_b128 v[196:199], v2 offset:28144
	s_waitcnt lgkmcnt(10)
	v_pk_fma_f32 v[142:143], v[150:151], v[210:211], v[142:143] op_sel_hi:[1,0,1]
	v_pk_fma_f32 v[144:145], v[152:153], v[210:211], v[144:145] op_sel_hi:[1,0,1]
	v_pk_fma_f32 v[146:147], v[154:155], v[210:211], v[146:147] op_sel_hi:[1,0,1]
	v_pk_fma_f32 v[148:149], v[156:157], v[210:211], v[148:149] op_sel_hi:[1,0,1]
	ds_read_b32 v212, v104 offset:28640
	ds_read_b128 v[166:169], v2 offset:27360
	s_waitcnt lgkmcnt(10)
	v_pk_fma_f32 v[96:97], v[96:97], v[126:127], v[142:143]
	v_pk_fma_f32 v[98:99], v[98:99], v[128:129], v[144:145]
	v_pk_fma_f32 v[100:101], v[100:101], v[130:131], v[146:147]
	v_pk_fma_f32 v[102:103], v[102:103], v[132:133], v[148:149]
	ds_read_b128 v[170:173], v2 offset:27376
	ds_read_b128 v[200:203], v2 offset:28384
	ds_read_b128 v[204:207], v2 offset:28400
	s_waitcnt lgkmcnt(9)
	v_pk_mul_f32 v[174:175], v[96:97], v[174:175]
	v_pk_mul_f32 v[158:159], v[96:97], v[158:159]
	v_pk_mul_f32 v[178:179], v[100:101], v[178:179]
	v_pk_mul_f32 v[162:163], v[100:101], v[162:163]
	v_pk_fma_f32 v[174:175], v[98:99], v[176:177], v[174:175]
	v_pk_fma_f32 v[158:159], v[98:99], v[160:161], v[158:159]
	v_pk_fma_f32 v[178:179], v[102:103], v[180:181], v[178:179]
	v_pk_fma_f32 v[162:163], v[102:103], v[164:165], v[162:163]
	v_pk_add_f32 v[174:175], v[174:175], v[178:179]
	v_pk_add_f32 v[158:159], v[158:159], v[162:163]
	v_add_f32_e32 v176, v174, v175
	v_add_f32_e32 v214, v158, v159
	ds_read_b128 v[134:137], v2 offset:29056
	v_add_f32_dpp v176, v176, v176 quad_perm:[1,0,3,2] row_mask:0xf bank_mask:0xf bound_ctrl:1
	ds_read_b128 v[138:141], v2 offset:29072
	ds_read_b128 v[142:145], v2 offset:29312
	v_add_f32_dpp v176, v176, v176 quad_perm:[2,3,0,1] row_mask:0xf bank_mask:0xf bound_ctrl:1
	ds_read_b128 v[146:149], v2 offset:29328
	ds_read_b128 v[150:153], v2 offset:29568
	v_add_f32_dpp v176, v176, v176 row_half_mirror row_mask:0xf bank_mask:0xf bound_ctrl:1
	s_waitcnt lgkmcnt(12)
	v_pk_mul_f32 v[182:183], v[182:183], v[176:177] op_sel_hi:[1,0]
	v_pk_mul_f32 v[184:185], v[184:185], v[176:177] op_sel_hi:[1,0]
	v_pk_mul_f32 v[186:187], v[186:187], v[176:177] op_sel_hi:[1,0]
	v_pk_mul_f32 v[188:189], v[188:189], v[176:177] op_sel_hi:[1,0]
	ds_read_b128 v[154:157], v2 offset:29584
	s_waitcnt lgkmcnt(10)
	v_pk_fma_f32 v[182:183], v[192:193], v[212:213], v[182:183] op_sel_hi:[1,0,1]
	v_pk_fma_f32 v[184:185], v[194:195], v[212:213], v[184:185] op_sel_hi:[1,0,1]
	v_pk_fma_f32 v[186:187], v[196:197], v[212:213], v[186:187] op_sel_hi:[1,0,1]
	v_pk_fma_f32 v[188:189], v[198:199], v[212:213], v[188:189] op_sel_hi:[1,0,1]
	ds_read_b32 v210, v104 offset:30080
	ds_read_b128 v[126:129], v2 offset:28800
	s_waitcnt lgkmcnt(10)
	v_pk_fma_f32 v[96:97], v[96:97], v[166:167], v[182:183]
	v_pk_fma_f32 v[98:99], v[98:99], v[168:169], v[184:185]
	v_pk_fma_f32 v[100:101], v[100:101], v[170:171], v[186:187]
	v_pk_fma_f32 v[102:103], v[102:103], v[172:173], v[188:189]
	ds_read_b128 v[130:133], v2 offset:28816
	ds_read_b128 v[158:161], v2 offset:29824
	ds_read_b128 v[162:165], v2 offset:29840
	s_waitcnt lgkmcnt(9)
	v_pk_mul_f32 v[134:135], v[96:97], v[134:135]
	v_pk_mul_f32 v[200:201], v[96:97], v[200:201]
	v_pk_mul_f32 v[138:139], v[100:101], v[138:139]
	v_pk_mul_f32 v[204:205], v[100:101], v[204:205]
	v_pk_fma_f32 v[134:135], v[98:99], v[136:137], v[134:135]
	v_pk_fma_f32 v[200:201], v[98:99], v[202:203], v[200:201]
	v_pk_fma_f32 v[138:139], v[102:103], v[140:141], v[138:139]
	v_pk_fma_f32 v[204:205], v[102:103], v[206:207], v[204:205]
	v_pk_add_f32 v[134:135], v[134:135], v[138:139]
	v_pk_add_f32 v[200:201], v[200:201], v[204:205]
	v_add_f32_e32 v136, v134, v135
	v_add_f32_e32 v215, v200, v201
	ds_read_b128 v[174:177], v2 offset:30496
	v_add_f32_dpp v136, v136, v136 quad_perm:[1,0,3,2] row_mask:0xf bank_mask:0xf bound_ctrl:1
	ds_read_b128 v[178:181], v2 offset:30512
	ds_read_b128 v[182:185], v2 offset:30752
	v_add_f32_dpp v136, v136, v136 quad_perm:[2,3,0,1] row_mask:0xf bank_mask:0xf bound_ctrl:1
	ds_read_b128 v[186:189], v2 offset:30768
	ds_read_b128 v[192:195], v2 offset:31008
	v_add_f32_dpp v136, v136, v136 row_half_mirror row_mask:0xf bank_mask:0xf bound_ctrl:1
	s_waitcnt lgkmcnt(12)
	v_pk_mul_f32 v[142:143], v[142:143], v[136:137] op_sel_hi:[1,0]
	v_pk_mul_f32 v[144:145], v[144:145], v[136:137] op_sel_hi:[1,0]
	v_pk_mul_f32 v[146:147], v[146:147], v[136:137] op_sel_hi:[1,0]
	v_pk_mul_f32 v[148:149], v[148:149], v[136:137] op_sel_hi:[1,0]
	ds_read_b128 v[196:199], v2 offset:31024
	s_waitcnt lgkmcnt(10)
	v_pk_fma_f32 v[142:143], v[150:151], v[210:211], v[142:143] op_sel_hi:[1,0,1]
	v_pk_fma_f32 v[144:145], v[152:153], v[210:211], v[144:145] op_sel_hi:[1,0,1]
	v_pk_fma_f32 v[146:147], v[154:155], v[210:211], v[146:147] op_sel_hi:[1,0,1]
	v_pk_fma_f32 v[148:149], v[156:157], v[210:211], v[148:149] op_sel_hi:[1,0,1]
	ds_read_b32 v212, v104 offset:31520
	ds_read_b128 v[166:169], v2 offset:30240
	s_waitcnt lgkmcnt(10)
	v_pk_fma_f32 v[96:97], v[96:97], v[126:127], v[142:143]
	v_pk_fma_f32 v[98:99], v[98:99], v[128:129], v[144:145]
	v_pk_fma_f32 v[100:101], v[100:101], v[130:131], v[146:147]
	v_pk_fma_f32 v[102:103], v[102:103], v[132:133], v[148:149]
	ds_read_b128 v[170:173], v2 offset:30256
	ds_read_b128 v[200:203], v2 offset:31264
	ds_read_b128 v[204:207], v2 offset:31280
	s_waitcnt lgkmcnt(9)
	v_pk_mul_f32 v[174:175], v[96:97], v[174:175]
	v_pk_mul_f32 v[158:159], v[96:97], v[158:159]
	v_pk_mul_f32 v[178:179], v[100:101], v[178:179]
	v_pk_mul_f32 v[162:163], v[100:101], v[162:163]
	v_pk_fma_f32 v[174:175], v[98:99], v[176:177], v[174:175]
	v_pk_fma_f32 v[158:159], v[98:99], v[160:161], v[158:159]
	v_pk_fma_f32 v[178:179], v[102:103], v[180:181], v[178:179]
	v_pk_fma_f32 v[162:163], v[102:103], v[164:165], v[162:163]
	v_pk_add_f32 v[174:175], v[174:175], v[178:179]
	v_pk_add_f32 v[158:159], v[158:159], v[162:163]
	v_add_f32_e32 v176, v174, v175
	v_add_f32_e32 v216, v158, v159
	ds_read_b128 v[134:137], v2 offset:31936
	v_add_f32_dpp v176, v176, v176 quad_perm:[1,0,3,2] row_mask:0xf bank_mask:0xf bound_ctrl:1
	ds_read_b128 v[138:141], v2 offset:31952
	ds_read_b128 v[142:145], v2 offset:32192
	v_add_f32_dpp v176, v176, v176 quad_perm:[2,3,0,1] row_mask:0xf bank_mask:0xf bound_ctrl:1
	ds_read_b128 v[146:149], v2 offset:32208
	ds_read_b128 v[150:153], v2 offset:32448
	v_add_f32_dpp v176, v176, v176 row_half_mirror row_mask:0xf bank_mask:0xf bound_ctrl:1
	s_waitcnt lgkmcnt(12)
	v_pk_mul_f32 v[182:183], v[182:183], v[176:177] op_sel_hi:[1,0]
	v_pk_mul_f32 v[184:185], v[184:185], v[176:177] op_sel_hi:[1,0]
	v_pk_mul_f32 v[186:187], v[186:187], v[176:177] op_sel_hi:[1,0]
	v_pk_mul_f32 v[188:189], v[188:189], v[176:177] op_sel_hi:[1,0]
	ds_read_b128 v[154:157], v2 offset:32464
	s_waitcnt lgkmcnt(10)
	v_pk_fma_f32 v[182:183], v[192:193], v[212:213], v[182:183] op_sel_hi:[1,0,1]
	v_pk_fma_f32 v[184:185], v[194:195], v[212:213], v[184:185] op_sel_hi:[1,0,1]
	v_pk_fma_f32 v[186:187], v[196:197], v[212:213], v[186:187] op_sel_hi:[1,0,1]
	v_pk_fma_f32 v[188:189], v[198:199], v[212:213], v[188:189] op_sel_hi:[1,0,1]
	ds_read_b32 v210, v104 offset:32960
	ds_read_b128 v[126:129], v2 offset:31680
	s_waitcnt lgkmcnt(10)
	v_pk_fma_f32 v[96:97], v[96:97], v[166:167], v[182:183]
	v_pk_fma_f32 v[98:99], v[98:99], v[168:169], v[184:185]
	v_pk_fma_f32 v[100:101], v[100:101], v[170:171], v[186:187]
	v_pk_fma_f32 v[102:103], v[102:103], v[172:173], v[188:189]
	ds_read_b128 v[130:133], v2 offset:31696
	ds_read_b128 v[158:161], v2 offset:32704
	ds_read_b128 v[162:165], v2 offset:32720
	s_waitcnt lgkmcnt(9)
	v_pk_mul_f32 v[134:135], v[96:97], v[134:135]
	v_pk_mul_f32 v[200:201], v[96:97], v[200:201]
	v_pk_mul_f32 v[138:139], v[100:101], v[138:139]
	v_pk_mul_f32 v[204:205], v[100:101], v[204:205]
	v_pk_fma_f32 v[134:135], v[98:99], v[136:137], v[134:135]
	v_pk_fma_f32 v[200:201], v[98:99], v[202:203], v[200:201]
	v_pk_fma_f32 v[138:139], v[102:103], v[140:141], v[138:139]
	v_pk_fma_f32 v[204:205], v[102:103], v[206:207], v[204:205]
	v_pk_add_f32 v[134:135], v[134:135], v[138:139]
	v_pk_add_f32 v[200:201], v[200:201], v[204:205]
	v_add_f32_e32 v136, v134, v135
	v_add_f32_e32 v208, v200, v201
	ds_read_b128 v[174:177], v2 offset:33376
	v_add_f32_dpp v136, v136, v136 quad_perm:[1,0,3,2] row_mask:0xf bank_mask:0xf bound_ctrl:1
	ds_read_b128 v[178:181], v2 offset:33392
	ds_read_b128 v[182:185], v2 offset:33632
	v_add_f32_dpp v136, v136, v136 quad_perm:[2,3,0,1] row_mask:0xf bank_mask:0xf bound_ctrl:1
	ds_read_b128 v[186:189], v2 offset:33648
	ds_read_b128 v[192:195], v2 offset:33888
	v_add_f32_dpp v136, v136, v136 row_half_mirror row_mask:0xf bank_mask:0xf bound_ctrl:1
	s_waitcnt lgkmcnt(12)
	v_pk_mul_f32 v[142:143], v[142:143], v[136:137] op_sel_hi:[1,0]
	v_pk_mul_f32 v[144:145], v[144:145], v[136:137] op_sel_hi:[1,0]
	v_pk_mul_f32 v[146:147], v[146:147], v[136:137] op_sel_hi:[1,0]
	v_pk_mul_f32 v[148:149], v[148:149], v[136:137] op_sel_hi:[1,0]
	ds_read_b128 v[196:199], v2 offset:33904
	s_waitcnt lgkmcnt(10)
	v_pk_fma_f32 v[142:143], v[150:151], v[210:211], v[142:143] op_sel_hi:[1,0,1]
	v_pk_fma_f32 v[144:145], v[152:153], v[210:211], v[144:145] op_sel_hi:[1,0,1]
	v_pk_fma_f32 v[146:147], v[154:155], v[210:211], v[146:147] op_sel_hi:[1,0,1]
	v_pk_fma_f32 v[148:149], v[156:157], v[210:211], v[148:149] op_sel_hi:[1,0,1]
	ds_read_b32 v212, v104 offset:34400
	ds_read_b128 v[166:169], v2 offset:33120
	s_waitcnt lgkmcnt(10)
	v_pk_fma_f32 v[96:97], v[96:97], v[126:127], v[142:143]
	v_pk_fma_f32 v[98:99], v[98:99], v[128:129], v[144:145]
	v_pk_fma_f32 v[100:101], v[100:101], v[130:131], v[146:147]
	v_pk_fma_f32 v[102:103], v[102:103], v[132:133], v[148:149]
	ds_read_b128 v[170:173], v2 offset:33136
	ds_read_b128 v[200:203], v2 offset:34144
	ds_read_b128 v[204:207], v2 offset:34160
	s_waitcnt lgkmcnt(9)
	v_pk_mul_f32 v[174:175], v[96:97], v[174:175]
	v_pk_mul_f32 v[158:159], v[96:97], v[158:159]
	v_pk_mul_f32 v[178:179], v[100:101], v[178:179]
	v_pk_mul_f32 v[162:163], v[100:101], v[162:163]
	v_pk_fma_f32 v[174:175], v[98:99], v[176:177], v[174:175]
	v_pk_fma_f32 v[158:159], v[98:99], v[160:161], v[158:159]
	v_pk_fma_f32 v[178:179], v[102:103], v[180:181], v[178:179]
	v_pk_fma_f32 v[162:163], v[102:103], v[164:165], v[162:163]
	v_pk_add_f32 v[174:175], v[174:175], v[178:179]
	v_pk_add_f32 v[158:159], v[158:159], v[162:163]
	v_add_f32_e32 v176, v174, v175
	v_add_f32_e32 v191, v158, v159
	ds_read_b128 v[134:137], v2 offset:34816
	v_add_f32_dpp v176, v176, v176 quad_perm:[1,0,3,2] row_mask:0xf bank_mask:0xf bound_ctrl:1
	ds_read_b128 v[138:141], v2 offset:34832
	ds_read_b128 v[142:145], v2 offset:35072
	v_add_f32_dpp v176, v176, v176 quad_perm:[2,3,0,1] row_mask:0xf bank_mask:0xf bound_ctrl:1
	ds_read_b128 v[146:149], v2 offset:35088
	ds_read_b128 v[150:153], v2 offset:35328
	v_add_f32_dpp v176, v176, v176 row_half_mirror row_mask:0xf bank_mask:0xf bound_ctrl:1
	s_waitcnt lgkmcnt(12)
	v_pk_mul_f32 v[182:183], v[182:183], v[176:177] op_sel_hi:[1,0]
	v_pk_mul_f32 v[184:185], v[184:185], v[176:177] op_sel_hi:[1,0]
	v_pk_mul_f32 v[186:187], v[186:187], v[176:177] op_sel_hi:[1,0]
	v_pk_mul_f32 v[188:189], v[188:189], v[176:177] op_sel_hi:[1,0]
	ds_read_b128 v[154:157], v2 offset:35344
	s_waitcnt lgkmcnt(10)
	v_pk_fma_f32 v[182:183], v[192:193], v[212:213], v[182:183] op_sel_hi:[1,0,1]
	v_pk_fma_f32 v[184:185], v[194:195], v[212:213], v[184:185] op_sel_hi:[1,0,1]
	v_pk_fma_f32 v[186:187], v[196:197], v[212:213], v[186:187] op_sel_hi:[1,0,1]
	v_pk_fma_f32 v[188:189], v[198:199], v[212:213], v[188:189] op_sel_hi:[1,0,1]
	ds_read_b32 v210, v104 offset:35840
	ds_read_b128 v[126:129], v2 offset:34560
	s_waitcnt lgkmcnt(10)
	v_pk_fma_f32 v[96:97], v[96:97], v[166:167], v[182:183]
	v_pk_fma_f32 v[98:99], v[98:99], v[168:169], v[184:185]
	v_pk_fma_f32 v[100:101], v[100:101], v[170:171], v[186:187]
	v_pk_fma_f32 v[102:103], v[102:103], v[172:173], v[188:189]
	ds_read_b128 v[130:133], v2 offset:34576
	ds_read_b128 v[158:161], v2 offset:35584
	ds_read_b128 v[162:165], v2 offset:35600
	s_waitcnt lgkmcnt(9)
	v_pk_mul_f32 v[134:135], v[96:97], v[134:135]
	v_pk_mul_f32 v[200:201], v[96:97], v[200:201]
	v_pk_mul_f32 v[138:139], v[100:101], v[138:139]
	v_pk_mul_f32 v[204:205], v[100:101], v[204:205]
	v_pk_fma_f32 v[134:135], v[98:99], v[136:137], v[134:135]
	v_pk_fma_f32 v[200:201], v[98:99], v[202:203], v[200:201]
	v_pk_fma_f32 v[138:139], v[102:103], v[140:141], v[138:139]
	v_pk_fma_f32 v[204:205], v[102:103], v[206:207], v[204:205]
	v_pk_add_f32 v[134:135], v[134:135], v[138:139]
	v_pk_add_f32 v[200:201], v[200:201], v[204:205]
	v_add_f32_e32 v136, v134, v135
	v_add_f32_e32 v59, v200, v201
	ds_read_b128 v[174:177], v2 offset:36256
	v_add_f32_dpp v136, v136, v136 quad_perm:[1,0,3,2] row_mask:0xf bank_mask:0xf bound_ctrl:1
	ds_read_b128 v[178:181], v2 offset:36272
	ds_read_b128 v[182:185], v2 offset:36512
	v_add_f32_dpp v136, v136, v136 quad_perm:[2,3,0,1] row_mask:0xf bank_mask:0xf bound_ctrl:1
	ds_read_b128 v[186:189], v2 offset:36528
	ds_read_b128 v[192:195], v2 offset:36768
	v_add_f32_dpp v136, v136, v136 row_half_mirror row_mask:0xf bank_mask:0xf bound_ctrl:1
	v_cndmask_b32_e64 v200, v213, v211, s[10:11]
	v_cndmask_b32_e64 v204, v211, v213, s[10:11]
	v_cndmask_b32_e64 v201, v215, v214, s[10:11]
	v_cndmask_b32_e64 v205, v214, v215, s[10:11]
	v_cndmask_b32_e64 v202, v208, v216, s[10:11]
	v_cndmask_b32_e64 v206, v216, v208, s[10:11]
	v_cndmask_b32_e64 v203, v59, v191, s[10:11]
	v_cndmask_b32_e64 v207, v191, v59, s[10:11]
	v_add_f32_dpp v200, v204, v200 quad_perm:[1,0,3,2] row_mask:0xf bank_mask:0xf bound_ctrl:1
	v_add_f32_dpp v201, v205, v201 quad_perm:[1,0,3,2] row_mask:0xf bank_mask:0xf bound_ctrl:1
	v_add_f32_dpp v202, v206, v202 quad_perm:[1,0,3,2] row_mask:0xf bank_mask:0xf bound_ctrl:1
	v_add_f32_dpp v203, v207, v203 quad_perm:[1,0,3,2] row_mask:0xf bank_mask:0xf bound_ctrl:1
	v_cndmask_b32_e64 v204, v201, v200, s[12:13]
	v_cndmask_b32_e64 v206, v200, v201, s[12:13]
	v_cndmask_b32_e64 v205, v203, v202, s[12:13]
	v_cndmask_b32_e64 v207, v202, v203, s[12:13]
	v_add_f32_dpp v204, v206, v204 quad_perm:[2,3,0,1] row_mask:0xf bank_mask:0xf bound_ctrl:1
	s_nop 0
	v_add_f32_dpp v205, v207, v205 quad_perm:[2,3,0,1] row_mask:0xf bank_mask:0xf bound_ctrl:1
	v_xor_b32_e32 v202, 4, v121
	v_cndmask_b32_e64 v200, v205, v204, s[14:15]
	v_cndmask_b32_e64 v201, v204, v205, s[14:15]
	v_lshlrev_b32_e32 v202, 2, v202
	ds_bpermute_b32 v201, v202, v201
	s_waitcnt lgkmcnt(0)
	v_add_f32_e32 v200, v200, v201
	ds_write_b32 v105, v200 offset:2048
	v_pk_mul_f32 v[142:143], v[142:143], v[136:137] op_sel_hi:[1,0]
	v_pk_mul_f32 v[144:145], v[144:145], v[136:137] op_sel_hi:[1,0]
	v_pk_mul_f32 v[146:147], v[146:147], v[136:137] op_sel_hi:[1,0]
	v_pk_mul_f32 v[148:149], v[148:149], v[136:137] op_sel_hi:[1,0]
	ds_read_b128 v[196:199], v2 offset:36784
	v_pk_fma_f32 v[142:143], v[150:151], v[210:211], v[142:143] op_sel_hi:[1,0,1]
	v_pk_fma_f32 v[144:145], v[152:153], v[210:211], v[144:145] op_sel_hi:[1,0,1]
	v_pk_fma_f32 v[146:147], v[154:155], v[210:211], v[146:147] op_sel_hi:[1,0,1]
	v_pk_fma_f32 v[148:149], v[156:157], v[210:211], v[148:149] op_sel_hi:[1,0,1]
	ds_read_b32 v212, v104 offset:37280
	ds_read_b128 v[166:169], v2 offset:36000
	v_pk_fma_f32 v[96:97], v[96:97], v[126:127], v[142:143]
	v_pk_fma_f32 v[98:99], v[98:99], v[128:129], v[144:145]
	v_pk_fma_f32 v[100:101], v[100:101], v[130:131], v[146:147]
	v_pk_fma_f32 v[102:103], v[102:103], v[132:133], v[148:149]
	ds_read_b128 v[170:173], v2 offset:36016
	ds_read_b128 v[200:203], v2 offset:37024
	ds_read_b128 v[204:207], v2 offset:37040
	v_pk_mul_f32 v[174:175], v[96:97], v[174:175]
	v_pk_mul_f32 v[158:159], v[96:97], v[158:159]
	v_pk_mul_f32 v[178:179], v[100:101], v[178:179]
	v_pk_mul_f32 v[162:163], v[100:101], v[162:163]
	v_pk_fma_f32 v[174:175], v[98:99], v[176:177], v[174:175]
	v_pk_fma_f32 v[158:159], v[98:99], v[160:161], v[158:159]
	v_pk_fma_f32 v[178:179], v[102:103], v[180:181], v[178:179]
	v_pk_fma_f32 v[162:163], v[102:103], v[164:165], v[162:163]
	v_pk_add_f32 v[174:175], v[174:175], v[178:179]
	v_pk_add_f32 v[158:159], v[158:159], v[162:163]
	v_add_f32_e32 v176, v174, v175
	v_add_f32_e32 v211, v158, v159
	ds_read_b128 v[134:137], v2 offset:37696
	v_add_f32_dpp v176, v176, v176 quad_perm:[1,0,3,2] row_mask:0xf bank_mask:0xf bound_ctrl:1
	ds_read_b128 v[138:141], v2 offset:37712
	ds_read_b128 v[142:145], v2 offset:37952
	v_add_f32_dpp v176, v176, v176 quad_perm:[2,3,0,1] row_mask:0xf bank_mask:0xf bound_ctrl:1
	ds_read_b128 v[146:149], v2 offset:37968
	ds_read_b128 v[150:153], v2 offset:38208
	v_add_f32_dpp v176, v176, v176 row_half_mirror row_mask:0xf bank_mask:0xf bound_ctrl:1
	v_pk_mul_f32 v[182:183], v[182:183], v[176:177] op_sel_hi:[1,0]
	v_pk_mul_f32 v[184:185], v[184:185], v[176:177] op_sel_hi:[1,0]
	v_pk_mul_f32 v[186:187], v[186:187], v[176:177] op_sel_hi:[1,0]
	v_pk_mul_f32 v[188:189], v[188:189], v[176:177] op_sel_hi:[1,0]
	ds_read_b128 v[154:157], v2 offset:38224
	s_waitcnt lgkmcnt(10)
	v_pk_fma_f32 v[182:183], v[192:193], v[212:213], v[182:183] op_sel_hi:[1,0,1]
	v_pk_fma_f32 v[184:185], v[194:195], v[212:213], v[184:185] op_sel_hi:[1,0,1]
	v_pk_fma_f32 v[186:187], v[196:197], v[212:213], v[186:187] op_sel_hi:[1,0,1]
	v_pk_fma_f32 v[188:189], v[198:199], v[212:213], v[188:189] op_sel_hi:[1,0,1]
	ds_read_b32 v210, v104 offset:38720
	ds_read_b128 v[126:129], v2 offset:37440
	s_waitcnt lgkmcnt(10)
	v_pk_fma_f32 v[96:97], v[96:97], v[166:167], v[182:183]
	v_pk_fma_f32 v[98:99], v[98:99], v[168:169], v[184:185]
	v_pk_fma_f32 v[100:101], v[100:101], v[170:171], v[186:187]
	v_pk_fma_f32 v[102:103], v[102:103], v[172:173], v[188:189]
	ds_read_b128 v[130:133], v2 offset:37456
	ds_read_b128 v[158:161], v2 offset:38464
	ds_read_b128 v[162:165], v2 offset:38480
	s_waitcnt lgkmcnt(9)
	v_pk_mul_f32 v[134:135], v[96:97], v[134:135]
	v_pk_mul_f32 v[200:201], v[96:97], v[200:201]
	v_pk_mul_f32 v[138:139], v[100:101], v[138:139]
	v_pk_mul_f32 v[204:205], v[100:101], v[204:205]
	v_pk_fma_f32 v[134:135], v[98:99], v[136:137], v[134:135]
	v_pk_fma_f32 v[200:201], v[98:99], v[202:203], v[200:201]
	v_pk_fma_f32 v[138:139], v[102:103], v[140:141], v[138:139]
	v_pk_fma_f32 v[204:205], v[102:103], v[206:207], v[204:205]
	v_pk_add_f32 v[134:135], v[134:135], v[138:139]
	v_pk_add_f32 v[200:201], v[200:201], v[204:205]
	v_add_f32_e32 v136, v134, v135
	v_add_f32_e32 v213, v200, v201
	ds_read_b128 v[174:177], v2 offset:39136
	v_add_f32_dpp v136, v136, v136 quad_perm:[1,0,3,2] row_mask:0xf bank_mask:0xf bound_ctrl:1
	ds_read_b128 v[178:181], v2 offset:39152
	ds_read_b128 v[182:185], v2 offset:39392
	v_add_f32_dpp v136, v136, v136 quad_perm:[2,3,0,1] row_mask:0xf bank_mask:0xf bound_ctrl:1
	ds_read_b128 v[186:189], v2 offset:39408
	ds_read_b128 v[192:195], v2 offset:39648
	v_add_f32_dpp v136, v136, v136 row_half_mirror row_mask:0xf bank_mask:0xf bound_ctrl:1
	s_waitcnt lgkmcnt(12)
	v_pk_mul_f32 v[142:143], v[142:143], v[136:137] op_sel_hi:[1,0]
	v_pk_mul_f32 v[144:145], v[144:145], v[136:137] op_sel_hi:[1,0]
	v_pk_mul_f32 v[146:147], v[146:147], v[136:137] op_sel_hi:[1,0]
	v_pk_mul_f32 v[148:149], v[148:149], v[136:137] op_sel_hi:[1,0]
	ds_read_b128 v[196:199], v2 offset:39664
	s_waitcnt lgkmcnt(10)
	v_pk_fma_f32 v[142:143], v[150:151], v[210:211], v[142:143] op_sel_hi:[1,0,1]
	v_pk_fma_f32 v[144:145], v[152:153], v[210:211], v[144:145] op_sel_hi:[1,0,1]
	v_pk_fma_f32 v[146:147], v[154:155], v[210:211], v[146:147] op_sel_hi:[1,0,1]
	v_pk_fma_f32 v[148:149], v[156:157], v[210:211], v[148:149] op_sel_hi:[1,0,1]
	ds_read_b32 v212, v104 offset:40160
	ds_read_b128 v[166:169], v2 offset:38880
	s_waitcnt lgkmcnt(10)
	v_pk_fma_f32 v[96:97], v[96:97], v[126:127], v[142:143]
	v_pk_fma_f32 v[98:99], v[98:99], v[128:129], v[144:145]
	v_pk_fma_f32 v[100:101], v[100:101], v[130:131], v[146:147]
	v_pk_fma_f32 v[102:103], v[102:103], v[132:133], v[148:149]
	ds_read_b128 v[170:173], v2 offset:38896
	ds_read_b128 v[200:203], v2 offset:39904
	ds_read_b128 v[204:207], v2 offset:39920
	s_waitcnt lgkmcnt(9)
	v_pk_mul_f32 v[174:175], v[96:97], v[174:175]
	v_pk_mul_f32 v[158:159], v[96:97], v[158:159]
	v_pk_mul_f32 v[178:179], v[100:101], v[178:179]
	v_pk_mul_f32 v[162:163], v[100:101], v[162:163]
	v_pk_fma_f32 v[174:175], v[98:99], v[176:177], v[174:175]
	v_pk_fma_f32 v[158:159], v[98:99], v[160:161], v[158:159]
	v_pk_fma_f32 v[178:179], v[102:103], v[180:181], v[178:179]
	v_pk_fma_f32 v[162:163], v[102:103], v[164:165], v[162:163]
	v_pk_add_f32 v[174:175], v[174:175], v[178:179]
	v_pk_add_f32 v[158:159], v[158:159], v[162:163]
	v_add_f32_e32 v176, v174, v175
	v_add_f32_e32 v214, v158, v159
	ds_read_b128 v[134:137], v2 offset:40576
	v_add_f32_dpp v176, v176, v176 quad_perm:[1,0,3,2] row_mask:0xf bank_mask:0xf bound_ctrl:1
	ds_read_b128 v[138:141], v2 offset:40592
	ds_read_b128 v[142:145], v2 offset:40832
	v_add_f32_dpp v176, v176, v176 quad_perm:[2,3,0,1] row_mask:0xf bank_mask:0xf bound_ctrl:1
	ds_read_b128 v[146:149], v2 offset:40848
	ds_read_b128 v[150:153], v2 offset:41088
	v_add_f32_dpp v176, v176, v176 row_half_mirror row_mask:0xf bank_mask:0xf bound_ctrl:1
	s_waitcnt lgkmcnt(12)
	v_pk_mul_f32 v[182:183], v[182:183], v[176:177] op_sel_hi:[1,0]
	v_pk_mul_f32 v[184:185], v[184:185], v[176:177] op_sel_hi:[1,0]
	v_pk_mul_f32 v[186:187], v[186:187], v[176:177] op_sel_hi:[1,0]
	v_pk_mul_f32 v[188:189], v[188:189], v[176:177] op_sel_hi:[1,0]
	ds_read_b128 v[154:157], v2 offset:41104
	s_waitcnt lgkmcnt(10)
	v_pk_fma_f32 v[182:183], v[192:193], v[212:213], v[182:183] op_sel_hi:[1,0,1]
	v_pk_fma_f32 v[184:185], v[194:195], v[212:213], v[184:185] op_sel_hi:[1,0,1]
	v_pk_fma_f32 v[186:187], v[196:197], v[212:213], v[186:187] op_sel_hi:[1,0,1]
	v_pk_fma_f32 v[188:189], v[198:199], v[212:213], v[188:189] op_sel_hi:[1,0,1]
	ds_read_b32 v210, v104 offset:41600
	ds_read_b128 v[126:129], v2 offset:40320
	s_waitcnt lgkmcnt(10)
	v_pk_fma_f32 v[96:97], v[96:97], v[166:167], v[182:183]
	v_pk_fma_f32 v[98:99], v[98:99], v[168:169], v[184:185]
	v_pk_fma_f32 v[100:101], v[100:101], v[170:171], v[186:187]
	v_pk_fma_f32 v[102:103], v[102:103], v[172:173], v[188:189]
	ds_read_b128 v[130:133], v2 offset:40336
	ds_read_b128 v[158:161], v2 offset:41344
	ds_read_b128 v[162:165], v2 offset:41360
	s_waitcnt lgkmcnt(9)
	v_pk_mul_f32 v[134:135], v[96:97], v[134:135]
	v_pk_mul_f32 v[200:201], v[96:97], v[200:201]
	v_pk_mul_f32 v[138:139], v[100:101], v[138:139]
	v_pk_mul_f32 v[204:205], v[100:101], v[204:205]
	v_pk_fma_f32 v[134:135], v[98:99], v[136:137], v[134:135]
	v_pk_fma_f32 v[200:201], v[98:99], v[202:203], v[200:201]
	v_pk_fma_f32 v[138:139], v[102:103], v[140:141], v[138:139]
	v_pk_fma_f32 v[204:205], v[102:103], v[206:207], v[204:205]
	v_pk_add_f32 v[134:135], v[134:135], v[138:139]
	v_pk_add_f32 v[200:201], v[200:201], v[204:205]
	v_add_f32_e32 v136, v134, v135
	v_add_f32_e32 v215, v200, v201
	ds_read_b128 v[174:177], v2 offset:42016
	v_add_f32_dpp v136, v136, v136 quad_perm:[1,0,3,2] row_mask:0xf bank_mask:0xf bound_ctrl:1
	ds_read_b128 v[178:181], v2 offset:42032
	ds_read_b128 v[182:185], v2 offset:42272
	v_add_f32_dpp v136, v136, v136 quad_perm:[2,3,0,1] row_mask:0xf bank_mask:0xf bound_ctrl:1
	ds_read_b128 v[186:189], v2 offset:42288
	ds_read_b128 v[192:195], v2 offset:42528
	v_add_f32_dpp v136, v136, v136 row_half_mirror row_mask:0xf bank_mask:0xf bound_ctrl:1
	s_waitcnt lgkmcnt(12)
	v_pk_mul_f32 v[142:143], v[142:143], v[136:137] op_sel_hi:[1,0]
	v_pk_mul_f32 v[144:145], v[144:145], v[136:137] op_sel_hi:[1,0]
	v_pk_mul_f32 v[146:147], v[146:147], v[136:137] op_sel_hi:[1,0]
	v_pk_mul_f32 v[148:149], v[148:149], v[136:137] op_sel_hi:[1,0]
	ds_read_b128 v[196:199], v2 offset:42544
	s_waitcnt lgkmcnt(10)
	v_pk_fma_f32 v[142:143], v[150:151], v[210:211], v[142:143] op_sel_hi:[1,0,1]
	v_pk_fma_f32 v[144:145], v[152:153], v[210:211], v[144:145] op_sel_hi:[1,0,1]
	v_pk_fma_f32 v[146:147], v[154:155], v[210:211], v[146:147] op_sel_hi:[1,0,1]
	v_pk_fma_f32 v[148:149], v[156:157], v[210:211], v[148:149] op_sel_hi:[1,0,1]
	ds_read_b32 v212, v104 offset:43040
	ds_read_b128 v[166:169], v2 offset:41760
	s_waitcnt lgkmcnt(10)
	v_pk_fma_f32 v[96:97], v[96:97], v[126:127], v[142:143]
	v_pk_fma_f32 v[98:99], v[98:99], v[128:129], v[144:145]
	v_pk_fma_f32 v[100:101], v[100:101], v[130:131], v[146:147]
	v_pk_fma_f32 v[102:103], v[102:103], v[132:133], v[148:149]
	ds_read_b128 v[170:173], v2 offset:41776
	ds_read_b128 v[200:203], v2 offset:42784
	ds_read_b128 v[204:207], v2 offset:42800
	s_waitcnt lgkmcnt(9)
	v_pk_mul_f32 v[174:175], v[96:97], v[174:175]
	v_pk_mul_f32 v[158:159], v[96:97], v[158:159]
	v_pk_mul_f32 v[178:179], v[100:101], v[178:179]
	v_pk_mul_f32 v[162:163], v[100:101], v[162:163]
	v_pk_fma_f32 v[174:175], v[98:99], v[176:177], v[174:175]
	v_pk_fma_f32 v[158:159], v[98:99], v[160:161], v[158:159]
	v_pk_fma_f32 v[178:179], v[102:103], v[180:181], v[178:179]
	v_pk_fma_f32 v[162:163], v[102:103], v[164:165], v[162:163]
	v_pk_add_f32 v[174:175], v[174:175], v[178:179]
	v_pk_add_f32 v[158:159], v[158:159], v[162:163]
	v_add_f32_e32 v176, v174, v175
	v_add_f32_e32 v216, v158, v159
	ds_read_b128 v[134:137], v2 offset:43456
	v_add_f32_dpp v176, v176, v176 quad_perm:[1,0,3,2] row_mask:0xf bank_mask:0xf bound_ctrl:1
	ds_read_b128 v[138:141], v2 offset:43472
	ds_read_b128 v[142:145], v2 offset:43712
	v_add_f32_dpp v176, v176, v176 quad_perm:[2,3,0,1] row_mask:0xf bank_mask:0xf bound_ctrl:1
	ds_read_b128 v[146:149], v2 offset:43728
	ds_read_b128 v[150:153], v2 offset:43968
	v_add_f32_dpp v176, v176, v176 row_half_mirror row_mask:0xf bank_mask:0xf bound_ctrl:1
	s_waitcnt lgkmcnt(12)
	v_pk_mul_f32 v[182:183], v[182:183], v[176:177] op_sel_hi:[1,0]
	v_pk_mul_f32 v[184:185], v[184:185], v[176:177] op_sel_hi:[1,0]
	v_pk_mul_f32 v[186:187], v[186:187], v[176:177] op_sel_hi:[1,0]
	v_pk_mul_f32 v[188:189], v[188:189], v[176:177] op_sel_hi:[1,0]
	ds_read_b128 v[154:157], v2 offset:43984
	s_waitcnt lgkmcnt(10)
	v_pk_fma_f32 v[182:183], v[192:193], v[212:213], v[182:183] op_sel_hi:[1,0,1]
	v_pk_fma_f32 v[184:185], v[194:195], v[212:213], v[184:185] op_sel_hi:[1,0,1]
	v_pk_fma_f32 v[186:187], v[196:197], v[212:213], v[186:187] op_sel_hi:[1,0,1]
	v_pk_fma_f32 v[188:189], v[198:199], v[212:213], v[188:189] op_sel_hi:[1,0,1]
	ds_read_b32 v210, v104 offset:44480
	ds_read_b128 v[126:129], v2 offset:43200
	s_waitcnt lgkmcnt(10)
	v_pk_fma_f32 v[96:97], v[96:97], v[166:167], v[182:183]
	v_pk_fma_f32 v[98:99], v[98:99], v[168:169], v[184:185]
	v_pk_fma_f32 v[100:101], v[100:101], v[170:171], v[186:187]
	v_pk_fma_f32 v[102:103], v[102:103], v[172:173], v[188:189]
	ds_read_b128 v[130:133], v2 offset:43216
	ds_read_b128 v[158:161], v2 offset:44224
	ds_read_b128 v[162:165], v2 offset:44240
	s_waitcnt lgkmcnt(9)
	v_pk_mul_f32 v[134:135], v[96:97], v[134:135]
	v_pk_mul_f32 v[200:201], v[96:97], v[200:201]
	v_pk_mul_f32 v[138:139], v[100:101], v[138:139]
	v_pk_mul_f32 v[204:205], v[100:101], v[204:205]
	v_pk_fma_f32 v[134:135], v[98:99], v[136:137], v[134:135]
	v_pk_fma_f32 v[200:201], v[98:99], v[202:203], v[200:201]
	v_pk_fma_f32 v[138:139], v[102:103], v[140:141], v[138:139]
	v_pk_fma_f32 v[204:205], v[102:103], v[206:207], v[204:205]
	v_pk_add_f32 v[134:135], v[134:135], v[138:139]
	v_pk_add_f32 v[200:201], v[200:201], v[204:205]
	v_add_f32_e32 v136, v134, v135
	v_add_f32_e32 v208, v200, v201
	ds_read_b128 v[174:177], v2 offset:44896
	v_add_f32_dpp v136, v136, v136 quad_perm:[1,0,3,2] row_mask:0xf bank_mask:0xf bound_ctrl:1
	ds_read_b128 v[178:181], v2 offset:44912
	ds_read_b128 v[182:185], v2 offset:45152
	v_add_f32_dpp v136, v136, v136 quad_perm:[2,3,0,1] row_mask:0xf bank_mask:0xf bound_ctrl:1
	ds_read_b128 v[186:189], v2 offset:45168
	ds_read_b128 v[192:195], v2 offset:45408
	v_add_f32_dpp v136, v136, v136 row_half_mirror row_mask:0xf bank_mask:0xf bound_ctrl:1
	s_waitcnt lgkmcnt(12)
	v_pk_mul_f32 v[142:143], v[142:143], v[136:137] op_sel_hi:[1,0]
	v_pk_mul_f32 v[144:145], v[144:145], v[136:137] op_sel_hi:[1,0]
	v_pk_mul_f32 v[146:147], v[146:147], v[136:137] op_sel_hi:[1,0]
	v_pk_mul_f32 v[148:149], v[148:149], v[136:137] op_sel_hi:[1,0]
	ds_read_b128 v[196:199], v2 offset:45424
	s_waitcnt lgkmcnt(10)
	v_pk_fma_f32 v[142:143], v[150:151], v[210:211], v[142:143] op_sel_hi:[1,0,1]
	v_pk_fma_f32 v[144:145], v[152:153], v[210:211], v[144:145] op_sel_hi:[1,0,1]
	v_pk_fma_f32 v[146:147], v[154:155], v[210:211], v[146:147] op_sel_hi:[1,0,1]
	v_pk_fma_f32 v[148:149], v[156:157], v[210:211], v[148:149] op_sel_hi:[1,0,1]
	ds_read_b32 v212, v104 offset:45920
	ds_read_b128 v[166:169], v2 offset:44640
	s_waitcnt lgkmcnt(10)
	v_pk_fma_f32 v[96:97], v[96:97], v[126:127], v[142:143]
	v_pk_fma_f32 v[98:99], v[98:99], v[128:129], v[144:145]
	v_pk_fma_f32 v[100:101], v[100:101], v[130:131], v[146:147]
	v_pk_fma_f32 v[102:103], v[102:103], v[132:133], v[148:149]
	ds_read_b128 v[170:173], v2 offset:44656
	ds_read_b128 v[200:203], v2 offset:45664
	ds_read_b128 v[204:207], v2 offset:45680
	s_waitcnt lgkmcnt(0)
	v_pk_mul_f32 v[174:175], v[96:97], v[174:175]
	v_pk_mul_f32 v[158:159], v[96:97], v[158:159]
	v_pk_mul_f32 v[178:179], v[100:101], v[178:179]
	v_pk_mul_f32 v[162:163], v[100:101], v[162:163]
	v_pk_fma_f32 v[174:175], v[98:99], v[176:177], v[174:175]
	v_pk_fma_f32 v[158:159], v[98:99], v[160:161], v[158:159]
	v_pk_fma_f32 v[178:179], v[102:103], v[180:181], v[178:179]
	v_pk_fma_f32 v[162:163], v[102:103], v[164:165], v[162:163]
	v_pk_add_f32 v[174:175], v[174:175], v[178:179]
	v_pk_add_f32 v[158:159], v[158:159], v[162:163]
	v_add_f32_e32 v176, v174, v175
	v_add_f32_e32 v191, v158, v159
	s_nop 0
	v_add_f32_dpp v176, v176, v176 quad_perm:[1,0,3,2] row_mask:0xf bank_mask:0xf bound_ctrl:1
	s_nop 1
	v_add_f32_dpp v176, v176, v176 quad_perm:[2,3,0,1] row_mask:0xf bank_mask:0xf bound_ctrl:1
	s_nop 1
	v_add_f32_dpp v176, v176, v176 row_half_mirror row_mask:0xf bank_mask:0xf bound_ctrl:1
	v_pk_mul_f32 v[182:183], v[182:183], v[176:177] op_sel_hi:[1,0]
	v_pk_mul_f32 v[184:185], v[184:185], v[176:177] op_sel_hi:[1,0]
	v_pk_mul_f32 v[186:187], v[186:187], v[176:177] op_sel_hi:[1,0]
	v_pk_mul_f32 v[188:189], v[188:189], v[176:177] op_sel_hi:[1,0]
	v_pk_fma_f32 v[182:183], v[192:193], v[212:213], v[182:183] op_sel_hi:[1,0,1]
	v_pk_fma_f32 v[184:185], v[194:195], v[212:213], v[184:185] op_sel_hi:[1,0,1]
	v_pk_fma_f32 v[186:187], v[196:197], v[212:213], v[186:187] op_sel_hi:[1,0,1]
	v_pk_fma_f32 v[188:189], v[198:199], v[212:213], v[188:189] op_sel_hi:[1,0,1]
	v_pk_fma_f32 v[96:97], v[96:97], v[166:167], v[182:183]
	v_pk_fma_f32 v[98:99], v[98:99], v[168:169], v[184:185]
	v_pk_fma_f32 v[100:101], v[100:101], v[170:171], v[186:187]
	v_pk_fma_f32 v[102:103], v[102:103], v[172:173], v[188:189]
	v_pk_mul_f32 v[200:201], v[96:97], v[200:201]
	v_pk_mul_f32 v[204:205], v[100:101], v[204:205]
	v_pk_fma_f32 v[200:201], v[98:99], v[202:203], v[200:201]
	v_pk_fma_f32 v[204:205], v[102:103], v[206:207], v[204:205]
	s_nop 0
	v_pk_add_f32 v[200:201], v[200:201], v[204:205]
	s_nop 0
	v_add_f32_e32 v59, v200, v201
	v_cndmask_b32_e64 v200, v213, v211, s[10:11]
	v_cndmask_b32_e64 v204, v211, v213, s[10:11]
	v_cndmask_b32_e64 v201, v215, v214, s[10:11]
	v_cndmask_b32_e64 v205, v214, v215, s[10:11]
	v_cndmask_b32_e64 v202, v208, v216, s[10:11]
	v_cndmask_b32_e64 v206, v216, v208, s[10:11]
	v_cndmask_b32_e64 v203, v59, v191, s[10:11]
	v_cndmask_b32_e64 v207, v191, v59, s[10:11]
	v_add_f32_dpp v200, v204, v200 quad_perm:[1,0,3,2] row_mask:0xf bank_mask:0xf bound_ctrl:1
	v_add_f32_dpp v201, v205, v201 quad_perm:[1,0,3,2] row_mask:0xf bank_mask:0xf bound_ctrl:1
	v_add_f32_dpp v202, v206, v202 quad_perm:[1,0,3,2] row_mask:0xf bank_mask:0xf bound_ctrl:1
	v_add_f32_dpp v203, v207, v203 quad_perm:[1,0,3,2] row_mask:0xf bank_mask:0xf bound_ctrl:1
	v_cndmask_b32_e64 v204, v201, v200, s[12:13]
	v_cndmask_b32_e64 v206, v200, v201, s[12:13]
	v_cndmask_b32_e64 v205, v203, v202, s[12:13]
	v_cndmask_b32_e64 v207, v202, v203, s[12:13]
	v_add_f32_dpp v204, v206, v204 quad_perm:[2,3,0,1] row_mask:0xf bank_mask:0xf bound_ctrl:1
	s_nop 0
	v_add_f32_dpp v205, v207, v205 quad_perm:[2,3,0,1] row_mask:0xf bank_mask:0xf bound_ctrl:1
	v_xor_b32_e32 v202, 4, v121
	v_cndmask_b32_e64 v200, v205, v204, s[14:15]
	v_cndmask_b32_e64 v201, v204, v205, s[14:15]
	v_lshlrev_b32_e32 v202, 2, v202
	ds_bpermute_b32 v201, v202, v201
	s_waitcnt lgkmcnt(0)
	v_add_f32_e32 v200, v200, v201
	ds_write_b32 v105, v200 offset:3072
	s_setprio 0

.LBB0_1102:
	v_lshrrev_b32_e32 v205, 6, v190
	s_nop 0
	v_readfirstlane_b32 s4, v205
	s_nop 3
	s_cmp_ge_u32 s4, 4
	s_cbranch_scc0 .Latt_prio
	s_setprio 1
